# ffn_up epilogue: the tile's conv weights staged in LDS by LDS-DMA one tile ahead (each wave for itself, double buffer) and read from LDS, replacing 12 broadcast-heavy global loads per wave per tile
# speedup vs baseline: 1.0088x; 1.0003x over previous
; #define PG8_STAGE(bufoff, gbase, voff) do { _Pragma("unroll") for (int _i = 0; _i < 2; ++_i) \
;         __builtin_amdgcn_global_load_lds((const unsigned*)((const char*)(gbase) + (voff)[_i]), (PG8_LAS unsigned*)(lds + (bufoff) + ldsw + _i * 8192), 16, 0, 0); } while (0)
; #define PG8_WAIT_V(n) asm volatile("s_waitcnt vmcnt(" #n ")" ::: "memory")
; #define PG8_BAR __builtin_amdgcn_s_barrier()
; template <class Epi, class Sched, bool ALIGN_EPI = false, bool SP2 = false>
; __device__ __forceinline__ void gemm_phase(PG8_LAS unsigned char* lds, const Gemm g, const Sched& S, const Epi& E) {
;     ...
;     const char* cA = (const char*)g.A + (size_t)cur.pm * tstep; const char* cB = (const char*)g.Bt + (size_t)cur.pn * tstep;
;     S.a_ready(cur);
;     if constexpr (SP2) {
;         PG8_STAGE(PG8_SB(0, 0), cB, voffB); PG8_STAGE(PG8_SB(0, 1), cB + hstep, voffB); PG8_STAGE(PG8_SA(0, 0), cA, voffA); PG8_STAGE(PG8_SA(0, 1), cA + hstep, voffA);
;         if (wr == 1) PG8_BAR;
;         PG8_WAIT_V(2); PG8_BAR;
;         PG8_STAGE(PG8_SB(1, 0), cB + kstep, voffB); PG8_STAGE(PG8_SA(1, 0), cA + kstep, voffA); PG8_STAGE(PG8_SB(1, 1), cB + hstep + kstep, voffB);
;         PG8_WAIT_V(6); PG8_BAR;
;     } else {
;         PG8_STAGE(PG8_SB(0, 0), cB, voffB); PG8_STAGE(PG8_SA(0, 0), cA, voffA); PG8_STAGE(PG8_SB(0, 1), cB + hstep, voffB); PG8_STAGE(PG8_SA(0, 1), cA + hstep, voffA);
;         if (wr == 1) PG8_BAR;
;         PG8_WAIT_V(4); PG8_BAR;
;         PG8_STAGE(PG8_SB(1, 0), cB + kstep, voffB); PG8_STAGE(PG8_SA(1, 0), cA + kstep, voffA); PG8_STAGE(PG8_SB(1, 1), cB + hstep + kstep, voffB);
;         PG8_WAIT_V(6); PG8_BAR;
;     }
.LBB0_1879:
	s_add_u32 s14, s6, 0x2ea00000
	v_readlane_b32 s9, v255, 4
	s_addc_u32 s15, s7, 0
	s_mul_i32 s9, s9, 0x21000
	s_add_u32 s40, s4, s9
	v_lshrrev_b32_e32 v15, 1, v12
	s_addc_u32 s41, s5, 0
	v_and_b32_e32 v15, 24, v15
	s_add_u32 s16, s6, 0x47800000
	v_and_b32_e32 v178, 15, v12
	v_lshlrev_b32_e32 v16, 1, v15
	v_lshlrev_b32_e32 v12, 2, v12
	s_addc_u32 s17, s7, 0
	v_lshl_or_b32 v16, v178, 6, v16
	s_lshl_b32 s4, s34, 13
	v_and_b32_e32 v12, 32, v12
	v_bitop3_b32 v17, v16, s4, v12 bitop3:0xde
	s_lshl_b32 s4, s18, 5
	s_add_i32 s92, s37, 0x18000
	s_and_b32 s9, s4, 0x60
	s_add_i32 s93, s92, s1
	s_add_i32 s91, s37, 0x20000
	s_lshl_b32 s4, s9, 7
	v_lshl_add_u64 v[4:5], v[4:5], 0, s[66:67]
	s_mov_b32 m0, s93
	s_add_i32 s94, s93, 0x2000
	s_add_i32 s95, s82, 0x8000
	s_add_i32 s96, s82, 0xa000
	v_bitop3_b32 v236, v16, s4, v12 bitop3:0xde
	s_waitcnt vmcnt(2)
	s_barrier
	global_load_lds_dwordx4 v[4:5], off
	v_lshl_add_u64 v[2:3], v[2:3], 0, s[66:67]
	s_mov_b32 m0, s94
	s_add_u32 s4, s76, 0x80080
	global_load_lds_dwordx4 v[2:3], off
	v_lshl_add_u64 v[0:1], v[0:1], 0, s[66:67]
	s_mov_b32 m0, s95
	s_addc_u32 s5, s77, 0
	s_add_i32 s97, s37, 0x1c000
	global_load_lds_dwordx4 v[0:1], off
	v_lshl_add_u64 v[0:1], v[6:7], 0, s[66:67]
	s_mov_b32 m0, s96
	s_add_i32 s33, s97, s1
	global_load_lds_dwordx4 v[0:1], off
	v_lshl_add_u64 v[0:1], s[4:5], 0, v[172:173]
	s_mov_b32 m0, s33
	s_add_i32 s1, s33, 0x2000
	global_load_lds_dwordx4 v[0:1], off
	v_lshl_add_u64 v[0:1], s[4:5], 0, v[176:177]
	s_mov_b32 m0, s1
	s_cmpk_lt_u32 s0, 0x100
	global_load_lds_dwordx4 v[0:1], off
	s_cselect_b64 s[18:19], -1, 0
	v_cmp_gt_u32_e32 vcc, 2, v178
	s_cmp_lg_u32 s34, 3
	v_or_b32_e32 v180, s9, v15
	s_cselect_b64 s[20:21], -1, 0
	s_lshl_b32 s9, s34, 9
	s_and_b64 s[22:23], s[18:19], vcc
	s_add_i32 s11, s34, 2
	v_mov_b32_e32 v0, 0xfffff200
	s_cmp_lg_u32 s11, 3
	v_lshl_add_u32 v0, v178, 8, v0
	s_cselect_b64 s[24:25], -1, 0
	s_lshl_b32 s12, s11, 9
	v_add_u32_e32 v1, s9, v0
	v_add_u32_e32 v0, s12, v0
	s_cmp_eq_u32 s11, 0
	v_or_b32_e32 v1, v180, v1
	v_or_b32_e32 v0, v0, v180
	s_cselect_b64 s[26:27], -1, 0
	v_lshlrev_b32_e32 v2, 2, v1
	v_lshlrev_b32_e32 v3, 2, v0
	s_and_b64 s[26:27], s[26:27], vcc
	v_cmp_eq_u32_e32 vcc, 0, v178
	v_mov_b32_e32 v0, 0x3fffff00
	v_mov_b32_e32 v1, 0x3ffffe00
	v_cndmask_b32_e32 v0, v0, v1, vcc
	v_add_u32_e32 v1, s9, v0
	v_or_b32_e32 v4, v180, v1
	v_add_u32_e32 v0, s12, v0
	v_lshlrev_b32_e32 v237, 2, v4
	v_or_b32_e32 v4, v0, v180
	v_lshlrev_b32_e32 v238, 2, v4
	v_or_b32_e32 v4, 4, v180
	v_or_b32_e32 v1, v4, v1
	v_or_b32_e32 v0, v4, v0
	v_lshlrev_b32_e32 v128, 2, v15
	v_lshlrev_b32_e32 v250, 2, v1
	v_lshlrev_b32_e32 v251, 2, v0
	v_lshl_add_u64 v[0:1], s[6:7], 0, v[128:129]
	s_mov_b64 s[6:7], 0x40c00000
	v_lshl_add_u64 v[188:189], v[0:1], 0, s[6:7]
	v_lshlrev_b32_e32 v0, 15, v8
	v_and_b32_e32 v0, 0xffff0000, v0
	v_lshl_add_u32 v0, v9, 12, v0
	v_and_b32_e32 v1, 1, v8
	s_cmp_gt_i32 s34, 0
	v_lshl_or_b32 v0, v1, 6, v0
	s_cselect_b64 s[28:29], -1, 0
	s_lshl_b32 s13, s34, 11
	v_lshl_add_u32 v190, v10, 1, v0
	v_lshlrev_b32_e32 v0, 15, v11
	s_cmp_gt_i32 s34, -2
	v_and_b32_e32 v0, 0xffff0000, v0
	v_lshl_or_b32 v181, s34, 6, v178
	s_waitcnt vmcnt(6)
	s_cselect_b64 s[34:35], -1, 0
	s_lshl_b32 s9, s11, 11
	v_lshl_add_u32 v0, v13, 12, v0
	v_and_b32_e32 v1, 1, v11
	v_mov_b32_e32 v179, v129
	v_lshlrev_b32_e32 v184, 2, v180
	v_mov_b32_e32 v185, v129
	s_add_i32 s69, s91, s13
	s_add_i32 s36, s91, s9
	v_lshl_or_b32 v0, v1, 6, v0
	v_cmp_lt_u32_e64 s[4:5], 13, v178
	v_lshl_add_u64 v[182:183], v[178:179], 0, -12
	s_mov_b32 s0, 0
	v_lshlrev_b32_e32 v239, 2, v4
	s_ashr_i32 s51, s44, 31
	s_ashr_i32 s59, s39, 31
	v_lshl_add_u64 v[186:187], s[40:41], 0, v[184:185]
	s_add_i32 s61, s69, 0xfffffc00
	s_addk_i32 s69, 0xfe00
	s_add_i32 s56, s37, 0x20200
	s_add_i32 s80, s36, 0xfffffc00
	s_addk_i32 s36, 0xfe00
	v_mov_b32_e32 v191, v129
	v_lshl_add_u32 v192, v14, 1, v0
	v_mov_b32_e32 v193, v129
	v_add_u32_e32 v185, s37, v17
	v_add_u32_e32 v252, s91, v2
	v_add_u32_e32 v253, s91, v3
	v_writelane_b32 v255, -1, 40
	v_writelane_b32 v255, 0, 44
	s_barrier
	s_branch .LBB0_1882

;     __device__ __forceinline__ void operator()(const f32x4 (&acc)[2][2][4][2], const Unit& u, int wr, int wc, int fr, int fq) const {
;     ...
;             for (int bj = 0; bj < 2; ++bj)
; #pragma unroll
;                 for (int j = 0; j < 3; ++j) w[bj][j] = *(const f32x4*)(cw + j * 11264 + bj * 5632 + u.pn * 128 + cidx + 4 * n);
; template <class Epi, class Sched, bool ALIGN_EPI = false, bool SP2 = false>
; __device__ __forceinline__ void gemm_phase(PG8_LAS unsigned char* lds, const Gemm g, const Sched& S, const Epi& E) {
;     ...
;         const bool has_next = S.next(ui + 1, nxt);
;         const char* nA = has_next ? (const char*)g.A + (size_t)nxt.pm * tstep : cA; const char* nB = has_next ? (const char*)g.Bt + (size_t)nxt.pn * tstep : cB;
.LBB0_1888:
	v_readlane_b32 s74, v255, 44
	s_bitcmp1_b32 s74, 1
	s_cbranch_scc1 .Lupw_have
	s_and_b32 s74, s74, 1
	v_lshrrev_b32_e32 v131, 5, v254
	v_mul_u32_u24_e32 v131, 0x5800, v131
	v_and_b32_e32 v132, 31, v254
	v_lshl_add_u32 v131, v132, 4, v131
	s_lshl_b32 s48, s8, 9
	v_add_u32_e32 v132, s48, v131
	v_mov_b32_e32 v133, 0
	v_sub_co_u32_e32 v134, vcc, v186, v184
	v_subbrev_co_u32_e32 v135, vcc, 0, v187, vcc
	v_lshl_add_u64 v[134:135], v[134:135], 0, v[132:133]
	s_mul_i32 s48, s74, 0xc00
	s_add_i32 s48, s48, s91
	s_add_i32 s48, s48, 0x2400
	s_mov_b32 s49, m0
	s_mov_b32 s75, 0xb000
	s_mov_b32 m0, s48
	s_nop 0
	global_load_lds_dwordx4 v[134:135], off
	s_add_i32 s48, s48, 0x400
	v_add_co_u32_e32 v134, vcc, s75, v134
	v_addc_co_u32_e32 v135, vcc, 0, v135, vcc
	s_mov_b32 m0, s48
	s_nop 0
	global_load_lds_dwordx4 v[134:135], off
	s_add_i32 s48, s48, 0x400
	v_add_co_u32_e32 v134, vcc, s75, v134
	v_addc_co_u32_e32 v135, vcc, 0, v135, vcc
	s_mov_b32 m0, s48
	s_nop 0
	global_load_lds_dwordx4 v[134:135], off
	s_mov_b32 m0, s49
	s_waitcnt vmcnt(0)
.Lupw_have:
	s_and_b64 vcc, exec, s[6:7]
	s_cbranch_vccz .Lupw_nonext
	v_readlane_b32 s74, v255, 44
	s_and_b32 s74, s74, 1
	s_xor_b32 s74, s74, 1
	v_lshrrev_b32_e32 v131, 5, v254
	v_mul_u32_u24_e32 v131, 0x5800, v131
	v_and_b32_e32 v132, 31, v254
	v_lshl_add_u32 v131, v132, 4, v131
	s_lshl_b32 s48, s40, 9
	v_add_u32_e32 v132, s48, v131
	v_mov_b32_e32 v133, 0
	v_sub_co_u32_e32 v134, vcc, v186, v184
	v_subbrev_co_u32_e32 v135, vcc, 0, v187, vcc
	v_lshl_add_u64 v[134:135], v[134:135], 0, v[132:133]
	s_mul_i32 s48, s74, 0xc00
	s_add_i32 s48, s48, s91
	s_add_i32 s48, s48, 0x2400
	s_mov_b32 s49, m0
	s_mov_b32 s75, 0xb000
	s_mov_b32 m0, s48
	s_nop 0
	global_load_lds_dwordx4 v[134:135], off
	s_add_i32 s48, s48, 0x400
	v_add_co_u32_e32 v134, vcc, s75, v134
	v_addc_co_u32_e32 v135, vcc, 0, v135, vcc
	s_mov_b32 m0, s48
	s_nop 0
	global_load_lds_dwordx4 v[134:135], off
	s_add_i32 s48, s48, 0x400
	v_add_co_u32_e32 v134, vcc, s75, v134
	v_addc_co_u32_e32 v135, vcc, 0, v135, vcc
	s_mov_b32 m0, s48
	s_nop 0
	global_load_lds_dwordx4 v[134:135], off
	s_mov_b32 m0, s49

; #define PG8_LAS __attribute__((address_space(3)))
;     __device__ __forceinline__ void operator()(const f32x4 (&acc)[2][2][4][2], const Unit& u, int wr, int wc, int fr, int fq) const {
;     ...
;         asm volatile("s_waitcnt lgkmcnt(0)" ::: "memory"); __builtin_amdgcn_s_barrier(); asm volatile("" ::: "memory");
; #pragma unroll
;         for (int n = 0; n < 2; ++n) {
;             f32x4 w[2][3];
; #pragma unroll
;             for (int bj = 0; bj < 2; ++bj)
; #pragma unroll
;                 for (int j = 0; j < 3; ++j) w[bj][j] = *(const f32x4*)(cw + j * 11264 + bj * 5632 + u.pn * 128 + cidx + 4 * n);
; #pragma unroll
;             for (int ai = 0; ai < 2; ++ai) {
;                 const int gi = ai * 2 + wr;
;                 f32x4 o1[2], o2[2];
; #pragma unroll
;                 for (int bj = 0; bj < 2; ++bj) {
;                     o1[bj] = (f32x4){0.f, 0.f, 0.f, 0.f}; o2[bj] = o1[bj];
;                     if (gi > 0) { o1[bj] = *(const PG8_LAS f32x4*)(xch + (((((gi - 1) * 2 + 1) * 2 + bj) * 128) + cidx + 4 * n) * 4);
;                                   o2[bj] = *(const PG8_LAS f32x4*)(xch + (((((gi - 1) * 2 + (fr == 0 ? 0 : 1)) * 2 + bj) * 128) + cidx + 4 * n) * 4); }
.LBB0_1910:
	s_or_b64 exec, exec, s[8:9]
	v_lshl_add_u64 v[222:223], s[10:11], 2, v[186:187]
	s_waitcnt lgkmcnt(0)
	s_barrier
	s_mov_b32 s9, 0
	v_readlane_b32 s8, v255, 44
	s_and_b32 s8, s8, 1
	s_mul_i32 s8, s8, 0xc00
	s_add_i32 s8, s8, s91
	s_add_i32 s8, s8, 0x2400
	v_add_u32_e32 v199, s8, v184
	ds_read_b128 v[130:133], v199
	ds_read_b128 v[134:137], v199 offset:1024
	ds_read_b128 v[138:141], v199 offset:2048
	ds_read_b128 v[142:145], v199 offset:512
	ds_read_b128 v[146:149], v199 offset:1536
	ds_read_b128 v[150:153], v199 offset:2560
	v_mov_b64_e32 v[234:235], s[14:15]
	v_mad_i64_i32 v[246:247], s[12:13], v228, s53, v[234:235]
	s_lshl_b64 s[74:75], s[10:11], 1
	v_lshl_add_u64 v[246:247], v[246:247], 0, s[74:75]
	v_lshlrev_b32_e32 v128, 1, v180
	v_lshl_add_u64 v[246:247], v[246:247], 0, v[128:129]
	s_and_b32 s8, s28, 0x800
	s_add_i32 s8, s8, s91
	s_addk_i32 s8, 0xf800
	v_add_u32_e32 v195, s8, v184
	v_cmp_eq_u32_e32 vcc, 14, v178
	v_add_u32_e32 v197, 0x400, v195
	v_cndmask_b32_e32 v197, v197, v195, vcc
	s_cmp_eq_u32 s28, 0
	s_cbranch_scc1 .Lupc_zero_b0
	ds_read_b128 v[154:157], v197
	ds_read_b128 v[158:161], v197 offset:512
	s_branch .Lupc_go_b0

; __device__ __forceinline__ unsigned cvt_pk_bf16(float lo, float hi) { unsigned r; asm volatile("v_cvt_pk_bf16_f32 %0, %1, %2" : "=v"(r) : "v"(lo), "v"(hi)); return r; }
;     static __device__ __forceinline__ float dpp_shr1(float old, float src) { return __builtin_bit_cast(float, __builtin_amdgcn_update_dpp(__builtin_bit_cast(int, old), __builtin_bit_cast(int, src), 0x111, 0xf, 0xf, false)); }
;     static __device__ __forceinline__ float dpp_shr2(float old, float src) { return __builtin_bit_cast(float, __builtin_amdgcn_update_dpp(__builtin_bit_cast(int, old), __builtin_bit_cast(int, src), 0x112, 0xf, 0xf, false)); }
;     static __device__ __forceinline__ float dpp_ror1(float src) { return __builtin_bit_cast(float, __builtin_amdgcn_update_dpp(0, __builtin_bit_cast(int, src), 0x121, 0xf, 0xf, true)); }
;     static __device__ __forceinline__ float dpp_ror2(float src) { return __builtin_bit_cast(float, __builtin_amdgcn_update_dpp(0, __builtin_bit_cast(int, src), 0x122, 0xf, 0xf, true)); }
;     __device__ __forceinline__ void operator()(const f32x4 (&acc)[2][2][4][2], const Unit& u, int wr, int wc, int fr, int fq) const {
;     ...
;                 for (int m = 0; m < 4; ++m) {
;                     f32x4 uu[2];
; #pragma unroll
;                     for (int bj = 0; bj < 2; ++bj) { const f32x4 cur = acc[ai][bj][m][n] * rs[ai][m];
; #pragma unroll
;                         for (int q = 0; q < 4; ++q) { const float p1 = dpp_shr1(o1[bj][q], cur[q]), p2 = dpp_shr2(o2[bj][q], cur[q]);
;                             uu[bj][q] = w[bj][0][q] * p2 + w[bj][1][q] * p1 + w[bj][2][q] * cur[q];
;                             o1[bj][q] = dpp_ror1(cur[q]); o2[bj][q] = dpp_ror2(cur[q]); } }
;                     u32x2v o;
;                     { const float a0 = uu[0][0] * __builtin_amdgcn_rcpf(1.f + __expf(-uu[0][0])) * uu[1][0], a1 = uu[0][1] * __builtin_amdgcn_rcpf(1.f + __expf(-uu[0][1])) * uu[1][1];
;                       const float a2 = uu[0][2] * __builtin_amdgcn_rcpf(1.f + __expf(-uu[0][2])) * uu[1][2], a3 = uu[0][3] * __builtin_amdgcn_rcpf(1.f + __expf(-uu[0][3])) * uu[1][3];
;                       o.x = cvt_pk_bf16(a0, a1); o.y = cvt_pk_bf16(a2, a3); }
;                     *(u32x2v*)(ACT + (size_t)(row0 + ai * HALF + m * 16) * 5632 + u.pn * 128 + cidx + 4 * n) = o;
.Lupc_go_b0:
	s_waitcnt lgkmcnt(0)
	v_pk_mul_f32 v[124:125], v[124:125], v[210:211] op_sel_hi:[1,0]
	v_pk_mul_f32 v[126:127], v[126:127], v[210:211] op_sel_hi:[1,0]
	v_pk_mul_f32 v[120:121], v[120:121], v[210:211] op_sel_hi:[1,0]
	v_pk_mul_f32 v[122:123], v[122:123], v[210:211] op_sel_hi:[1,0]
	v_pk_mul_f32 v[162:163], v[124:125], v[138:139]
	v_pk_mul_f32 v[164:165], v[126:127], v[140:141]
	v_pk_mul_f32 v[166:167], v[120:121], v[150:151]
	v_pk_mul_f32 v[168:169], v[122:123], v[152:153]
	v_fmac_f32_dpp v162, v124, v134 row_shr:1 row_mask:0xf bank_mask:0xf
	v_fmac_f32_dpp v163, v125, v135 row_shr:1 row_mask:0xf bank_mask:0xf
	v_fmac_f32_dpp v164, v126, v136 row_shr:1 row_mask:0xf bank_mask:0xf
	v_fmac_f32_dpp v165, v127, v137 row_shr:1 row_mask:0xf bank_mask:0xf
	v_fmac_f32_dpp v166, v120, v146 row_shr:1 row_mask:0xf bank_mask:0xf
	v_fmac_f32_dpp v167, v121, v147 row_shr:1 row_mask:0xf bank_mask:0xf
	v_fmac_f32_dpp v168, v122, v148 row_shr:1 row_mask:0xf bank_mask:0xf
	v_fmac_f32_dpp v169, v123, v149 row_shr:1 row_mask:0xf bank_mask:0xf
	v_fmac_f32_dpp v162, v124, v130 row_shr:2 row_mask:0xf bank_mask:0xf
	v_fmac_f32_dpp v163, v125, v131 row_shr:2 row_mask:0xf bank_mask:0xf
	v_fmac_f32_dpp v164, v126, v132 row_shr:2 row_mask:0xf bank_mask:0xf
	v_fmac_f32_dpp v165, v127, v133 row_shr:2 row_mask:0xf bank_mask:0xf
	v_fmac_f32_dpp v166, v120, v142 row_shr:2 row_mask:0xf bank_mask:0xf
	v_fmac_f32_dpp v167, v121, v143 row_shr:2 row_mask:0xf bank_mask:0xf
	v_fmac_f32_dpp v168, v122, v144 row_shr:2 row_mask:0xf bank_mask:0xf
	v_fmac_f32_dpp v169, v123, v145 row_shr:2 row_mask:0xf bank_mask:0xf
	v_fmac_f32_dpp v162, v154, v134 row_shl:15 row_mask:0xf bank_mask:0xf
	v_fmac_f32_dpp v163, v155, v135 row_shl:15 row_mask:0xf bank_mask:0xf
	v_fmac_f32_dpp v164, v156, v136 row_shl:15 row_mask:0xf bank_mask:0xf
	v_fmac_f32_dpp v165, v157, v137 row_shl:15 row_mask:0xf bank_mask:0xf
	v_fmac_f32_dpp v166, v158, v146 row_shl:15 row_mask:0xf bank_mask:0xf
	v_fmac_f32_dpp v167, v159, v147 row_shl:15 row_mask:0xf bank_mask:0xf
	v_fmac_f32_dpp v168, v160, v148 row_shl:15 row_mask:0xf bank_mask:0xf
	v_fmac_f32_dpp v169, v161, v149 row_shl:15 row_mask:0xf bank_mask:0xf
	v_fmac_f32_dpp v162, v154, v130 row_shl:14 row_mask:0xf bank_mask:0xf
	v_fmac_f32_dpp v163, v155, v131 row_shl:14 row_mask:0xf bank_mask:0xf
	v_fmac_f32_dpp v164, v156, v132 row_shl:14 row_mask:0xf bank_mask:0xf
	v_fmac_f32_dpp v165, v157, v133 row_shl:14 row_mask:0xf bank_mask:0xf
	v_fmac_f32_dpp v166, v158, v142 row_shl:14 row_mask:0xf bank_mask:0xf
	v_fmac_f32_dpp v167, v159, v143 row_shl:14 row_mask:0xf bank_mask:0xf
	v_fmac_f32_dpp v168, v160, v144 row_shl:14 row_mask:0xf bank_mask:0xf
	v_fmac_f32_dpp v169, v161, v145 row_shl:14 row_mask:0xf bank_mask:0xf
	v_mul_f32_e32 v230, 0xbfb8aa3b, v162
	v_mul_f32_e32 v231, 0xbfb8aa3b, v163
	v_mul_f32_e32 v232, 0xbfb8aa3b, v164
	v_mul_f32_e32 v233, 0xbfb8aa3b, v165
	v_exp_f32_e32 v230, v230
	v_exp_f32_e32 v231, v231
	v_exp_f32_e32 v232, v232
	v_exp_f32_e32 v233, v233
	v_add_f32_e32 v230, 1.0, v230
	v_add_f32_e32 v231, 1.0, v231
	v_add_f32_e32 v232, 1.0, v232
	v_add_f32_e32 v233, 1.0, v233
	v_rcp_f32_e32 v230, v230
	v_rcp_f32_e32 v231, v231
	v_rcp_f32_e32 v232, v232
	v_rcp_f32_e32 v233, v233
	v_mul_f32_e32 v230, v162, v230
	v_mul_f32_e32 v231, v163, v231
	v_mul_f32_e32 v232, v164, v232
	v_mul_f32_e32 v233, v165, v233
	v_mul_f32_e32 v230, v230, v166
	v_mul_f32_e32 v231, v231, v167
	v_mul_f32_e32 v232, v232, v168
	v_mul_f32_e32 v233, v233, v169
	v_cvt_pk_bf16_f32 v224, v230, v231
	v_cvt_pk_bf16_f32 v225, v232, v233
	ds_read_b128 v[154:157], v197 offset:4096
	ds_read_b128 v[158:161], v197 offset:4608
	v_pk_mul_f32 v[116:117], v[116:117], v[214:215] op_sel_hi:[1,0]
	v_pk_mul_f32 v[118:119], v[118:119], v[214:215] op_sel_hi:[1,0]
	v_pk_mul_f32 v[112:113], v[112:113], v[214:215] op_sel_hi:[1,0]
	v_pk_mul_f32 v[114:115], v[114:115], v[214:215] op_sel_hi:[1,0]
	v_pk_mul_f32 v[162:163], v[116:117], v[138:139]
	v_pk_mul_f32 v[164:165], v[118:119], v[140:141]
	v_pk_mul_f32 v[166:167], v[112:113], v[150:151]
	v_pk_mul_f32 v[168:169], v[114:115], v[152:153]
	v_fmac_f32_dpp v162, v116, v134 row_shr:1 row_mask:0xf bank_mask:0xf
	v_fmac_f32_dpp v163, v117, v135 row_shr:1 row_mask:0xf bank_mask:0xf
	v_fmac_f32_dpp v164, v118, v136 row_shr:1 row_mask:0xf bank_mask:0xf
	v_fmac_f32_dpp v165, v119, v137 row_shr:1 row_mask:0xf bank_mask:0xf
	v_fmac_f32_dpp v166, v112, v146 row_shr:1 row_mask:0xf bank_mask:0xf
	v_fmac_f32_dpp v167, v113, v147 row_shr:1 row_mask:0xf bank_mask:0xf
	v_fmac_f32_dpp v168, v114, v148 row_shr:1 row_mask:0xf bank_mask:0xf
	v_fmac_f32_dpp v169, v115, v149 row_shr:1 row_mask:0xf bank_mask:0xf
	v_fmac_f32_dpp v162, v116, v130 row_shr:2 row_mask:0xf bank_mask:0xf
	v_fmac_f32_dpp v163, v117, v131 row_shr:2 row_mask:0xf bank_mask:0xf
	v_fmac_f32_dpp v164, v118, v132 row_shr:2 row_mask:0xf bank_mask:0xf
	v_fmac_f32_dpp v165, v119, v133 row_shr:2 row_mask:0xf bank_mask:0xf
	v_fmac_f32_dpp v166, v112, v142 row_shr:2 row_mask:0xf bank_mask:0xf
	v_fmac_f32_dpp v167, v113, v143 row_shr:2 row_mask:0xf bank_mask:0xf
	v_fmac_f32_dpp v168, v114, v144 row_shr:2 row_mask:0xf bank_mask:0xf
	v_fmac_f32_dpp v169, v115, v145 row_shr:2 row_mask:0xf bank_mask:0xf
	v_fmac_f32_dpp v162, v124, v134 row_shl:15 row_mask:0xf bank_mask:0xf
	v_fmac_f32_dpp v163, v125, v135 row_shl:15 row_mask:0xf bank_mask:0xf
	v_fmac_f32_dpp v164, v126, v136 row_shl:15 row_mask:0xf bank_mask:0xf
	v_fmac_f32_dpp v165, v127, v137 row_shl:15 row_mask:0xf bank_mask:0xf
	v_fmac_f32_dpp v166, v120, v146 row_shl:15 row_mask:0xf bank_mask:0xf
	v_fmac_f32_dpp v167, v121, v147 row_shl:15 row_mask:0xf bank_mask:0xf
; __device__ __forceinline__ unsigned cvt_pk_bf16(float lo, float hi) { unsigned r; asm volatile("v_cvt_pk_bf16_f32 %0, %1, %2" : "=v"(r) : "v"(lo), "v"(hi)); return r; }
;     static __device__ __forceinline__ float dpp_shr1(float old, float src) { return __builtin_bit_cast(float, __builtin_amdgcn_update_dpp(__builtin_bit_cast(int, old), __builtin_bit_cast(int, src), 0x111, 0xf, 0xf, false)); }
;     static __device__ __forceinline__ float dpp_shr2(float old, float src) { return __builtin_bit_cast(float, __builtin_amdgcn_update_dpp(__builtin_bit_cast(int, old), __builtin_bit_cast(int, src), 0x112, 0xf, 0xf, false)); }
;     static __device__ __forceinline__ float dpp_ror1(float src) { return __builtin_bit_cast(float, __builtin_amdgcn_update_dpp(0, __builtin_bit_cast(int, src), 0x121, 0xf, 0xf, true)); }
;     static __device__ __forceinline__ float dpp_ror2(float src) { return __builtin_bit_cast(float, __builtin_amdgcn_update_dpp(0, __builtin_bit_cast(int, src), 0x122, 0xf, 0xf, true)); }
;     __device__ __forceinline__ void operator()(const f32x4 (&acc)[2][2][4][2], const Unit& u, int wr, int wc, int fr, int fq) const {
;     ...
;                 for (int m = 0; m < 4; ++m) {
;                     f32x4 uu[2];
; #pragma unroll
;                     for (int bj = 0; bj < 2; ++bj) { const f32x4 cur = acc[ai][bj][m][n] * rs[ai][m];
; #pragma unroll
;                         for (int q = 0; q < 4; ++q) { const float p1 = dpp_shr1(o1[bj][q], cur[q]), p2 = dpp_shr2(o2[bj][q], cur[q]);
;                             uu[bj][q] = w[bj][0][q] * p2 + w[bj][1][q] * p1 + w[bj][2][q] * cur[q];
;                             o1[bj][q] = dpp_ror1(cur[q]); o2[bj][q] = dpp_ror2(cur[q]); } }
;                     u32x2v o;
;                     { const float a0 = uu[0][0] * __builtin_amdgcn_rcpf(1.f + __expf(-uu[0][0])) * uu[1][0], a1 = uu[0][1] * __builtin_amdgcn_rcpf(1.f + __expf(-uu[0][1])) * uu[1][1];
;                       const float a2 = uu[0][2] * __builtin_amdgcn_rcpf(1.f + __expf(-uu[0][2])) * uu[1][2], a3 = uu[0][3] * __builtin_amdgcn_rcpf(1.f + __expf(-uu[0][3])) * uu[1][3];
;                       o.x = cvt_pk_bf16(a0, a1); o.y = cvt_pk_bf16(a2, a3); }
	v_fmac_f32_dpp v168, v122, v148 row_shl:15 row_mask:0xf bank_mask:0xf
	v_fmac_f32_dpp v169, v123, v149 row_shl:15 row_mask:0xf bank_mask:0xf
	v_fmac_f32_dpp v162, v124, v130 row_shl:14 row_mask:0xf bank_mask:0xf
	v_fmac_f32_dpp v163, v125, v131 row_shl:14 row_mask:0xf bank_mask:0xf
	v_fmac_f32_dpp v164, v126, v132 row_shl:14 row_mask:0xf bank_mask:0xf
	v_fmac_f32_dpp v165, v127, v133 row_shl:14 row_mask:0xf bank_mask:0xf
	v_fmac_f32_dpp v166, v120, v142 row_shl:14 row_mask:0xf bank_mask:0xf
	v_fmac_f32_dpp v167, v121, v143 row_shl:14 row_mask:0xf bank_mask:0xf
	v_fmac_f32_dpp v168, v122, v144 row_shl:14 row_mask:0xf bank_mask:0xf
	v_fmac_f32_dpp v169, v123, v145 row_shl:14 row_mask:0xf bank_mask:0xf
	v_mul_f32_e32 v230, 0xbfb8aa3b, v162
	v_mul_f32_e32 v231, 0xbfb8aa3b, v163
	v_mul_f32_e32 v232, 0xbfb8aa3b, v164
	v_mul_f32_e32 v233, 0xbfb8aa3b, v165
	v_exp_f32_e32 v230, v230
	v_exp_f32_e32 v231, v231
	v_exp_f32_e32 v232, v232
	v_exp_f32_e32 v233, v233
	v_add_f32_e32 v230, 1.0, v230
	v_add_f32_e32 v231, 1.0, v231
	v_add_f32_e32 v232, 1.0, v232
	v_add_f32_e32 v233, 1.0, v233
	v_rcp_f32_e32 v230, v230
	v_rcp_f32_e32 v231, v231
	v_rcp_f32_e32 v232, v232
	v_rcp_f32_e32 v233, v233
	v_mul_f32_e32 v230, v162, v230
	v_mul_f32_e32 v231, v163, v231
	v_mul_f32_e32 v232, v164, v232
	v_mul_f32_e32 v233, v165, v233
	v_mul_f32_e32 v230, v230, v166
	v_mul_f32_e32 v231, v231, v167
	v_mul_f32_e32 v232, v232, v168
	v_mul_f32_e32 v233, v233, v169
	v_cvt_pk_bf16_f32 v226, v230, v231
	v_cvt_pk_bf16_f32 v227, v232, v233
	v_pk_mul_f32 v[108:109], v[108:109], v[218:219] op_sel_hi:[1,0]
	v_pk_mul_f32 v[110:111], v[110:111], v[218:219] op_sel_hi:[1,0]
	v_pk_mul_f32 v[104:105], v[104:105], v[218:219] op_sel_hi:[1,0]
	v_pk_mul_f32 v[106:107], v[106:107], v[218:219] op_sel_hi:[1,0]
	v_pk_mul_f32 v[162:163], v[108:109], v[138:139]
	v_pk_mul_f32 v[164:165], v[110:111], v[140:141]
	v_pk_mul_f32 v[166:167], v[104:105], v[150:151]
	v_pk_mul_f32 v[168:169], v[106:107], v[152:153]
	v_fmac_f32_dpp v162, v108, v134 row_shr:1 row_mask:0xf bank_mask:0xf
	v_fmac_f32_dpp v163, v109, v135 row_shr:1 row_mask:0xf bank_mask:0xf
	v_fmac_f32_dpp v164, v110, v136 row_shr:1 row_mask:0xf bank_mask:0xf
	v_fmac_f32_dpp v165, v111, v137 row_shr:1 row_mask:0xf bank_mask:0xf
	v_fmac_f32_dpp v166, v104, v146 row_shr:1 row_mask:0xf bank_mask:0xf
	v_fmac_f32_dpp v167, v105, v147 row_shr:1 row_mask:0xf bank_mask:0xf
	v_fmac_f32_dpp v168, v106, v148 row_shr:1 row_mask:0xf bank_mask:0xf
	v_fmac_f32_dpp v169, v107, v149 row_shr:1 row_mask:0xf bank_mask:0xf
	v_fmac_f32_dpp v162, v108, v130 row_shr:2 row_mask:0xf bank_mask:0xf
	v_fmac_f32_dpp v163, v109, v131 row_shr:2 row_mask:0xf bank_mask:0xf
	v_fmac_f32_dpp v164, v110, v132 row_shr:2 row_mask:0xf bank_mask:0xf
	v_fmac_f32_dpp v165, v111, v133 row_shr:2 row_mask:0xf bank_mask:0xf
	v_fmac_f32_dpp v166, v104, v142 row_shr:2 row_mask:0xf bank_mask:0xf
	v_fmac_f32_dpp v167, v105, v143 row_shr:2 row_mask:0xf bank_mask:0xf
	v_fmac_f32_dpp v168, v106, v144 row_shr:2 row_mask:0xf bank_mask:0xf
	v_fmac_f32_dpp v169, v107, v145 row_shr:2 row_mask:0xf bank_mask:0xf
	v_fmac_f32_dpp v162, v116, v134 row_shl:15 row_mask:0xf bank_mask:0xf
	v_fmac_f32_dpp v163, v117, v135 row_shl:15 row_mask:0xf bank_mask:0xf
	v_fmac_f32_dpp v164, v118, v136 row_shl:15 row_mask:0xf bank_mask:0xf
	v_fmac_f32_dpp v165, v119, v137 row_shl:15 row_mask:0xf bank_mask:0xf
	v_fmac_f32_dpp v166, v112, v146 row_shl:15 row_mask:0xf bank_mask:0xf
	v_fmac_f32_dpp v167, v113, v147 row_shl:15 row_mask:0xf bank_mask:0xf
	v_fmac_f32_dpp v168, v114, v148 row_shl:15 row_mask:0xf bank_mask:0xf
	v_fmac_f32_dpp v169, v115, v149 row_shl:15 row_mask:0xf bank_mask:0xf
	v_fmac_f32_dpp v162, v116, v130 row_shl:14 row_mask:0xf bank_mask:0xf
	v_fmac_f32_dpp v163, v117, v131 row_shl:14 row_mask:0xf bank_mask:0xf
	v_fmac_f32_dpp v164, v118, v132 row_shl:14 row_mask:0xf bank_mask:0xf
	v_fmac_f32_dpp v165, v119, v133 row_shl:14 row_mask:0xf bank_mask:0xf
	v_fmac_f32_dpp v166, v112, v142 row_shl:14 row_mask:0xf bank_mask:0xf
	v_fmac_f32_dpp v167, v113, v143 row_shl:14 row_mask:0xf bank_mask:0xf
	v_fmac_f32_dpp v168, v114, v144 row_shl:14 row_mask:0xf bank_mask:0xf
	v_fmac_f32_dpp v169, v115, v145 row_shl:14 row_mask:0xf bank_mask:0xf
	v_mul_f32_e32 v230, 0xbfb8aa3b, v162
	v_mul_f32_e32 v231, 0xbfb8aa3b, v163
	v_mul_f32_e32 v232, 0xbfb8aa3b, v164
	v_mul_f32_e32 v233, 0xbfb8aa3b, v165
	v_exp_f32_e32 v230, v230
	v_exp_f32_e32 v231, v231
	v_exp_f32_e32 v232, v232
	v_exp_f32_e32 v233, v233
	v_add_f32_e32 v230, 1.0, v230
	v_add_f32_e32 v231, 1.0, v231
	v_add_f32_e32 v232, 1.0, v232
	v_add_f32_e32 v233, 1.0, v233
	v_rcp_f32_e32 v230, v230
	v_rcp_f32_e32 v231, v231
	v_rcp_f32_e32 v232, v232
	v_rcp_f32_e32 v233, v233
	v_mul_f32_e32 v230, v162, v230
	v_mul_f32_e32 v231, v163, v231
	v_mul_f32_e32 v232, v164, v232
	v_mul_f32_e32 v233, v165, v233
	v_mul_f32_e32 v230, v230, v166
	v_mul_f32_e32 v231, v231, v167
	v_mul_f32_e32 v232, v232, v168
	v_mul_f32_e32 v233, v233, v169
	v_cvt_pk_bf16_f32 v216, v230, v231
	v_cvt_pk_bf16_f32 v217, v232, v233
	v_pk_mul_f32 v[100:101], v[100:101], v[194:195] op_sel_hi:[1,0]
	v_pk_mul_f32 v[102:103], v[102:103], v[194:195] op_sel_hi:[1,0]
	v_pk_mul_f32 v[96:97], v[96:97], v[194:195] op_sel_hi:[1,0]
	v_pk_mul_f32 v[98:99], v[98:99], v[194:195] op_sel_hi:[1,0]
	v_pk_mul_f32 v[162:163], v[100:101], v[138:139]
	v_pk_mul_f32 v[164:165], v[102:103], v[140:141]
	v_pk_mul_f32 v[166:167], v[96:97], v[150:151]
	v_pk_mul_f32 v[168:169], v[98:99], v[152:153]
	v_fmac_f32_dpp v162, v100, v134 row_shr:1 row_mask:0xf bank_mask:0xf
	v_fmac_f32_dpp v163, v101, v135 row_shr:1 row_mask:0xf bank_mask:0xf
; #define PG8_LAS __attribute__((address_space(3)))
; __device__ __forceinline__ unsigned cvt_pk_bf16(float lo, float hi) { unsigned r; asm volatile("v_cvt_pk_bf16_f32 %0, %1, %2" : "=v"(r) : "v"(lo), "v"(hi)); return r; }
;     static __device__ __forceinline__ float dpp_ror1(float src) { return __builtin_bit_cast(float, __builtin_amdgcn_update_dpp(0, __builtin_bit_cast(int, src), 0x121, 0xf, 0xf, true)); }
;     __device__ __forceinline__ void operator()(const f32x4 (&acc)[2][2][4][2], const Unit& u, int wr, int wc, int fr, int fq) const {
;     ...
;             for (int bj = 0; bj < 2; ++bj)
; #pragma unroll
;                 for (int j = 0; j < 3; ++j) w[bj][j] = *(const f32x4*)(cw + j * 11264 + bj * 5632 + u.pn * 128 + cidx + 4 * n);
; #pragma unroll
;             for (int ai = 0; ai < 2; ++ai) {
;                 const int gi = ai * 2 + wr;
;                 f32x4 o1[2], o2[2];
; #pragma unroll
;                 for (int bj = 0; bj < 2; ++bj) {
;                     o1[bj] = (f32x4){0.f, 0.f, 0.f, 0.f}; o2[bj] = o1[bj];
;                     if (gi > 0) { o1[bj] = *(const PG8_LAS f32x4*)(xch + (((((gi - 1) * 2 + 1) * 2 + bj) * 128) + cidx + 4 * n) * 4);
;                                   o2[bj] = *(const PG8_LAS f32x4*)(xch + (((((gi - 1) * 2 + (fr == 0 ? 0 : 1)) * 2 + bj) * 128) + cidx + 4 * n) * 4); }
;                 }
; #pragma unroll
;                 for (int m = 0; m < 4; ++m) {
;                     f32x4 uu[2];
; #pragma unroll
;                     for (int bj = 0; bj < 2; ++bj) { const f32x4 cur = acc[ai][bj][m][n] * rs[ai][m];
; #pragma unroll
;                         for (int q = 0; q < 4; ++q) { const float p1 = dpp_shr1(o1[bj][q], cur[q]), p2 = dpp_shr2(o2[bj][q], cur[q]);
;                             uu[bj][q] = w[bj][0][q] * p2 + w[bj][1][q] * p1 + w[bj][2][q] * cur[q];
;                             o1[bj][q] = dpp_ror1(cur[q]); o2[bj][q] = dpp_ror2(cur[q]); } }
;                     u32x2v o;
;                     { const float a0 = uu[0][0] * __builtin_amdgcn_rcpf(1.f + __expf(-uu[0][0])) * uu[1][0], a1 = uu[0][1] * __builtin_amdgcn_rcpf(1.f + __expf(-uu[0][1])) * uu[1][1];
;                       const float a2 = uu[0][2] * __builtin_amdgcn_rcpf(1.f + __expf(-uu[0][2])) * uu[1][2], a3 = uu[0][3] * __builtin_amdgcn_rcpf(1.f + __expf(-uu[0][3])) * uu[1][3];
;                       o.x = cvt_pk_bf16(a0, a1); o.y = cvt_pk_bf16(a2, a3); }
	v_fmac_f32_dpp v164, v102, v136 row_shr:1 row_mask:0xf bank_mask:0xf
	v_fmac_f32_dpp v165, v103, v137 row_shr:1 row_mask:0xf bank_mask:0xf
	v_fmac_f32_dpp v166, v96, v146 row_shr:1 row_mask:0xf bank_mask:0xf
	v_fmac_f32_dpp v167, v97, v147 row_shr:1 row_mask:0xf bank_mask:0xf
	v_fmac_f32_dpp v168, v98, v148 row_shr:1 row_mask:0xf bank_mask:0xf
	v_fmac_f32_dpp v169, v99, v149 row_shr:1 row_mask:0xf bank_mask:0xf
	v_fmac_f32_dpp v162, v100, v130 row_shr:2 row_mask:0xf bank_mask:0xf
	v_fmac_f32_dpp v163, v101, v131 row_shr:2 row_mask:0xf bank_mask:0xf
	v_fmac_f32_dpp v164, v102, v132 row_shr:2 row_mask:0xf bank_mask:0xf
	v_fmac_f32_dpp v165, v103, v133 row_shr:2 row_mask:0xf bank_mask:0xf
	v_fmac_f32_dpp v166, v96, v142 row_shr:2 row_mask:0xf bank_mask:0xf
	v_fmac_f32_dpp v167, v97, v143 row_shr:2 row_mask:0xf bank_mask:0xf
	v_fmac_f32_dpp v168, v98, v144 row_shr:2 row_mask:0xf bank_mask:0xf
	v_fmac_f32_dpp v169, v99, v145 row_shr:2 row_mask:0xf bank_mask:0xf
	v_fmac_f32_dpp v162, v108, v134 row_shl:15 row_mask:0xf bank_mask:0xf
	v_fmac_f32_dpp v163, v109, v135 row_shl:15 row_mask:0xf bank_mask:0xf
	v_fmac_f32_dpp v164, v110, v136 row_shl:15 row_mask:0xf bank_mask:0xf
	v_fmac_f32_dpp v165, v111, v137 row_shl:15 row_mask:0xf bank_mask:0xf
	v_fmac_f32_dpp v166, v104, v146 row_shl:15 row_mask:0xf bank_mask:0xf
	v_fmac_f32_dpp v167, v105, v147 row_shl:15 row_mask:0xf bank_mask:0xf
	v_fmac_f32_dpp v168, v106, v148 row_shl:15 row_mask:0xf bank_mask:0xf
	v_fmac_f32_dpp v169, v107, v149 row_shl:15 row_mask:0xf bank_mask:0xf
	v_fmac_f32_dpp v162, v108, v130 row_shl:14 row_mask:0xf bank_mask:0xf
	v_fmac_f32_dpp v163, v109, v131 row_shl:14 row_mask:0xf bank_mask:0xf
	v_fmac_f32_dpp v164, v110, v132 row_shl:14 row_mask:0xf bank_mask:0xf
	v_fmac_f32_dpp v165, v111, v133 row_shl:14 row_mask:0xf bank_mask:0xf
	v_fmac_f32_dpp v166, v104, v142 row_shl:14 row_mask:0xf bank_mask:0xf
	v_fmac_f32_dpp v167, v105, v143 row_shl:14 row_mask:0xf bank_mask:0xf
	v_fmac_f32_dpp v168, v106, v144 row_shl:14 row_mask:0xf bank_mask:0xf
	v_fmac_f32_dpp v169, v107, v145 row_shl:14 row_mask:0xf bank_mask:0xf
	v_mul_f32_e32 v230, 0xbfb8aa3b, v162
	v_mul_f32_e32 v231, 0xbfb8aa3b, v163
	v_mul_f32_e32 v232, 0xbfb8aa3b, v164
	v_mul_f32_e32 v233, 0xbfb8aa3b, v165
	v_exp_f32_e32 v230, v230
	v_exp_f32_e32 v231, v231
	v_exp_f32_e32 v232, v232
	v_exp_f32_e32 v233, v233
	v_add_f32_e32 v230, 1.0, v230
	v_add_f32_e32 v231, 1.0, v231
	v_add_f32_e32 v232, 1.0, v232
	v_add_f32_e32 v233, 1.0, v233
	v_rcp_f32_e32 v230, v230
	v_rcp_f32_e32 v231, v231
	v_rcp_f32_e32 v232, v232
	v_rcp_f32_e32 v233, v233
	v_mul_f32_e32 v230, v162, v230
	v_mul_f32_e32 v231, v163, v231
	v_mul_f32_e32 v232, v164, v232
	v_mul_f32_e32 v233, v165, v233
	v_mul_f32_e32 v230, v230, v166
	v_mul_f32_e32 v231, v231, v167
	v_mul_f32_e32 v232, v232, v168
	v_mul_f32_e32 v233, v233, v169
	v_cvt_pk_bf16_f32 v220, v230, v231
	v_cvt_pk_bf16_f32 v221, v232, v233
	ds_read_b128 v[96:99], v199 offset:16
	ds_read_b128 v[100:103], v199 offset:1040
	ds_read_b128 v[104:107], v199 offset:2064
	ds_read_b128 v[108:111], v199 offset:528
	ds_read_b128 v[112:115], v199 offset:1552
	ds_read_b128 v[116:119], v199 offset:2576
	s_waitcnt lgkmcnt(0)
	v_pk_mul_f32 v[92:93], v[92:93], v[198:199] op_sel_hi:[1,0]
	v_pk_mul_f32 v[94:95], v[94:95], v[198:199] op_sel_hi:[1,0]
	v_pk_mul_f32 v[88:89], v[88:89], v[198:199] op_sel_hi:[1,0]
	v_pk_mul_f32 v[90:91], v[90:91], v[198:199] op_sel_hi:[1,0]
	v_pk_mul_f32 v[162:163], v[92:93], v[138:139]
	v_pk_mul_f32 v[164:165], v[94:95], v[140:141]
	v_pk_mul_f32 v[166:167], v[88:89], v[150:151]
	v_pk_mul_f32 v[168:169], v[90:91], v[152:153]
	v_fmac_f32_dpp v162, v92, v134 row_shr:1 row_mask:0xf bank_mask:0xf
	v_fmac_f32_dpp v163, v93, v135 row_shr:1 row_mask:0xf bank_mask:0xf
	v_fmac_f32_dpp v164, v94, v136 row_shr:1 row_mask:0xf bank_mask:0xf
	v_fmac_f32_dpp v165, v95, v137 row_shr:1 row_mask:0xf bank_mask:0xf
	v_fmac_f32_dpp v166, v88, v146 row_shr:1 row_mask:0xf bank_mask:0xf
	v_fmac_f32_dpp v167, v89, v147 row_shr:1 row_mask:0xf bank_mask:0xf
	v_fmac_f32_dpp v168, v90, v148 row_shr:1 row_mask:0xf bank_mask:0xf
	v_fmac_f32_dpp v169, v91, v149 row_shr:1 row_mask:0xf bank_mask:0xf
	v_fmac_f32_dpp v162, v92, v130 row_shr:2 row_mask:0xf bank_mask:0xf
	v_fmac_f32_dpp v163, v93, v131 row_shr:2 row_mask:0xf bank_mask:0xf
	v_fmac_f32_dpp v164, v94, v132 row_shr:2 row_mask:0xf bank_mask:0xf
	v_fmac_f32_dpp v165, v95, v133 row_shr:2 row_mask:0xf bank_mask:0xf
	v_fmac_f32_dpp v166, v88, v142 row_shr:2 row_mask:0xf bank_mask:0xf
	v_fmac_f32_dpp v167, v89, v143 row_shr:2 row_mask:0xf bank_mask:0xf
	v_fmac_f32_dpp v168, v90, v144 row_shr:2 row_mask:0xf bank_mask:0xf
	v_fmac_f32_dpp v169, v91, v145 row_shr:2 row_mask:0xf bank_mask:0xf
	v_fmac_f32_dpp v162, v154, v134 row_shl:15 row_mask:0xf bank_mask:0xf
	v_fmac_f32_dpp v163, v155, v135 row_shl:15 row_mask:0xf bank_mask:0xf
	v_fmac_f32_dpp v164, v156, v136 row_shl:15 row_mask:0xf bank_mask:0xf
	v_fmac_f32_dpp v165, v157, v137 row_shl:15 row_mask:0xf bank_mask:0xf
	v_fmac_f32_dpp v166, v158, v146 row_shl:15 row_mask:0xf bank_mask:0xf
	v_fmac_f32_dpp v167, v159, v147 row_shl:15 row_mask:0xf bank_mask:0xf
	v_fmac_f32_dpp v168, v160, v148 row_shl:15 row_mask:0xf bank_mask:0xf
	v_fmac_f32_dpp v169, v161, v149 row_shl:15 row_mask:0xf bank_mask:0xf
	v_fmac_f32_dpp v162, v154, v130 row_shl:14 row_mask:0xf bank_mask:0xf
	v_fmac_f32_dpp v163, v155, v131 row_shl:14 row_mask:0xf bank_mask:0xf
	v_fmac_f32_dpp v164, v156, v132 row_shl:14 row_mask:0xf bank_mask:0xf
	v_fmac_f32_dpp v165, v157, v133 row_shl:14 row_mask:0xf bank_mask:0xf
	v_fmac_f32_dpp v166, v158, v142 row_shl:14 row_mask:0xf bank_mask:0xf
	v_fmac_f32_dpp v167, v159, v143 row_shl:14 row_mask:0xf bank_mask:0xf
	v_fmac_f32_dpp v168, v160, v144 row_shl:14 row_mask:0xf bank_mask:0xf
	v_fmac_f32_dpp v169, v161, v145 row_shl:14 row_mask:0xf bank_mask:0xf
	v_mul_f32_e32 v230, 0xbfb8aa3b, v162
	v_mul_f32_e32 v231, 0xbfb8aa3b, v163
	v_mul_f32_e32 v232, 0xbfb8aa3b, v164
	v_mul_f32_e32 v233, 0xbfb8aa3b, v165
	v_exp_f32_e32 v230, v230
	v_exp_f32_e32 v231, v231
	v_exp_f32_e32 v232, v232
	v_exp_f32_e32 v233, v233
	v_add_f32_e32 v230, 1.0, v230
	v_add_f32_e32 v231, 1.0, v231
	v_add_f32_e32 v232, 1.0, v232
	v_add_f32_e32 v233, 1.0, v233
	v_rcp_f32_e32 v230, v230
	v_rcp_f32_e32 v231, v231
	v_rcp_f32_e32 v232, v232
	v_rcp_f32_e32 v233, v233
	v_mul_f32_e32 v230, v162, v230
	v_mul_f32_e32 v231, v163, v231
	v_mul_f32_e32 v232, v164, v232
	v_mul_f32_e32 v233, v165, v233
	v_mul_f32_e32 v230, v230, v166
	v_mul_f32_e32 v231, v231, v167
	v_mul_f32_e32 v232, v232, v168
	v_mul_f32_e32 v233, v233, v169
	v_cvt_pk_bf16_f32 v212, v230, v231
	v_cvt_pk_bf16_f32 v213, v232, v233
	s_cmp_eq_u32 s28, 0
	s_cbranch_scc1 .Lupc_zero_b2
	ds_read_b128 v[154:157], v197 offset:16
	ds_read_b128 v[158:161], v197 offset:528
	s_branch .Lupc_go_b2

; __device__ __forceinline__ unsigned cvt_pk_bf16(float lo, float hi) { unsigned r; asm volatile("v_cvt_pk_bf16_f32 %0, %1, %2" : "=v"(r) : "v"(lo), "v"(hi)); return r; }
;     static __device__ __forceinline__ float dpp_shr1(float old, float src) { return __builtin_bit_cast(float, __builtin_amdgcn_update_dpp(__builtin_bit_cast(int, old), __builtin_bit_cast(int, src), 0x111, 0xf, 0xf, false)); }
;     static __device__ __forceinline__ float dpp_shr2(float old, float src) { return __builtin_bit_cast(float, __builtin_amdgcn_update_dpp(__builtin_bit_cast(int, old), __builtin_bit_cast(int, src), 0x112, 0xf, 0xf, false)); }
;     static __device__ __forceinline__ float dpp_ror1(float src) { return __builtin_bit_cast(float, __builtin_amdgcn_update_dpp(0, __builtin_bit_cast(int, src), 0x121, 0xf, 0xf, true)); }
;     static __device__ __forceinline__ float dpp_ror2(float src) { return __builtin_bit_cast(float, __builtin_amdgcn_update_dpp(0, __builtin_bit_cast(int, src), 0x122, 0xf, 0xf, true)); }
;     __device__ __forceinline__ void operator()(const f32x4 (&acc)[2][2][4][2], const Unit& u, int wr, int wc, int fr, int fq) const {
;     ...
;                 for (int m = 0; m < 4; ++m) {
;                     f32x4 uu[2];
; #pragma unroll
;                     for (int bj = 0; bj < 2; ++bj) { const f32x4 cur = acc[ai][bj][m][n] * rs[ai][m];
; #pragma unroll
;                         for (int q = 0; q < 4; ++q) { const float p1 = dpp_shr1(o1[bj][q], cur[q]), p2 = dpp_shr2(o2[bj][q], cur[q]);
;                             uu[bj][q] = w[bj][0][q] * p2 + w[bj][1][q] * p1 + w[bj][2][q] * cur[q];
;                             o1[bj][q] = dpp_ror1(cur[q]); o2[bj][q] = dpp_ror2(cur[q]); } }
;                     u32x2v o;
;                     { const float a0 = uu[0][0] * __builtin_amdgcn_rcpf(1.f + __expf(-uu[0][0])) * uu[1][0], a1 = uu[0][1] * __builtin_amdgcn_rcpf(1.f + __expf(-uu[0][1])) * uu[1][1];
;                       const float a2 = uu[0][2] * __builtin_amdgcn_rcpf(1.f + __expf(-uu[0][2])) * uu[1][2], a3 = uu[0][3] * __builtin_amdgcn_rcpf(1.f + __expf(-uu[0][3])) * uu[1][3];
;                       o.x = cvt_pk_bf16(a0, a1); o.y = cvt_pk_bf16(a2, a3); }
.Lupc_go_b2:
	v_pk_mul_f32 v[84:85], v[84:85], v[202:203] op_sel_hi:[1,0]
	v_pk_mul_f32 v[86:87], v[86:87], v[202:203] op_sel_hi:[1,0]
	v_pk_mul_f32 v[80:81], v[80:81], v[202:203] op_sel_hi:[1,0]
	v_pk_mul_f32 v[82:83], v[82:83], v[202:203] op_sel_hi:[1,0]
	v_pk_mul_f32 v[162:163], v[84:85], v[138:139]
	v_pk_mul_f32 v[164:165], v[86:87], v[140:141]
	v_pk_mul_f32 v[166:167], v[80:81], v[150:151]
	v_pk_mul_f32 v[168:169], v[82:83], v[152:153]
	v_fmac_f32_dpp v162, v84, v134 row_shr:1 row_mask:0xf bank_mask:0xf
	v_fmac_f32_dpp v163, v85, v135 row_shr:1 row_mask:0xf bank_mask:0xf
	v_fmac_f32_dpp v164, v86, v136 row_shr:1 row_mask:0xf bank_mask:0xf
	v_fmac_f32_dpp v165, v87, v137 row_shr:1 row_mask:0xf bank_mask:0xf
	v_fmac_f32_dpp v166, v80, v146 row_shr:1 row_mask:0xf bank_mask:0xf
	v_fmac_f32_dpp v167, v81, v147 row_shr:1 row_mask:0xf bank_mask:0xf
	v_fmac_f32_dpp v168, v82, v148 row_shr:1 row_mask:0xf bank_mask:0xf
	v_fmac_f32_dpp v169, v83, v149 row_shr:1 row_mask:0xf bank_mask:0xf
	v_fmac_f32_dpp v162, v84, v130 row_shr:2 row_mask:0xf bank_mask:0xf
	v_fmac_f32_dpp v163, v85, v131 row_shr:2 row_mask:0xf bank_mask:0xf
	v_fmac_f32_dpp v164, v86, v132 row_shr:2 row_mask:0xf bank_mask:0xf
	v_fmac_f32_dpp v165, v87, v133 row_shr:2 row_mask:0xf bank_mask:0xf
	v_fmac_f32_dpp v166, v80, v142 row_shr:2 row_mask:0xf bank_mask:0xf
	v_fmac_f32_dpp v167, v81, v143 row_shr:2 row_mask:0xf bank_mask:0xf
	v_fmac_f32_dpp v168, v82, v144 row_shr:2 row_mask:0xf bank_mask:0xf
	v_fmac_f32_dpp v169, v83, v145 row_shr:2 row_mask:0xf bank_mask:0xf
	v_fmac_f32_dpp v162, v92, v134 row_shl:15 row_mask:0xf bank_mask:0xf
	v_fmac_f32_dpp v163, v93, v135 row_shl:15 row_mask:0xf bank_mask:0xf
	v_fmac_f32_dpp v164, v94, v136 row_shl:15 row_mask:0xf bank_mask:0xf
	v_fmac_f32_dpp v165, v95, v137 row_shl:15 row_mask:0xf bank_mask:0xf
	v_fmac_f32_dpp v166, v88, v146 row_shl:15 row_mask:0xf bank_mask:0xf
	v_fmac_f32_dpp v167, v89, v147 row_shl:15 row_mask:0xf bank_mask:0xf
	v_fmac_f32_dpp v168, v90, v148 row_shl:15 row_mask:0xf bank_mask:0xf
	v_fmac_f32_dpp v169, v91, v149 row_shl:15 row_mask:0xf bank_mask:0xf
	v_fmac_f32_dpp v162, v92, v130 row_shl:14 row_mask:0xf bank_mask:0xf
	v_fmac_f32_dpp v163, v93, v131 row_shl:14 row_mask:0xf bank_mask:0xf
	v_fmac_f32_dpp v164, v94, v132 row_shl:14 row_mask:0xf bank_mask:0xf
	v_fmac_f32_dpp v165, v95, v133 row_shl:14 row_mask:0xf bank_mask:0xf
	v_fmac_f32_dpp v166, v88, v142 row_shl:14 row_mask:0xf bank_mask:0xf
	v_fmac_f32_dpp v167, v89, v143 row_shl:14 row_mask:0xf bank_mask:0xf
	v_fmac_f32_dpp v168, v90, v144 row_shl:14 row_mask:0xf bank_mask:0xf
	v_fmac_f32_dpp v169, v91, v145 row_shl:14 row_mask:0xf bank_mask:0xf
	v_mul_f32_e32 v230, 0xbfb8aa3b, v162
	v_mul_f32_e32 v231, 0xbfb8aa3b, v163
	v_mul_f32_e32 v232, 0xbfb8aa3b, v164
	v_mul_f32_e32 v233, 0xbfb8aa3b, v165
	v_exp_f32_e32 v230, v230
	v_exp_f32_e32 v231, v231
	v_exp_f32_e32 v232, v232
	v_exp_f32_e32 v233, v233
	v_add_f32_e32 v230, 1.0, v230
	v_add_f32_e32 v231, 1.0, v231
	v_add_f32_e32 v232, 1.0, v232
	v_add_f32_e32 v233, 1.0, v233
	v_rcp_f32_e32 v230, v230
	v_rcp_f32_e32 v231, v231
	v_rcp_f32_e32 v232, v232
	v_rcp_f32_e32 v233, v233
	v_mul_f32_e32 v230, v162, v230
	v_mul_f32_e32 v231, v163, v231
	v_mul_f32_e32 v232, v164, v232
	v_mul_f32_e32 v233, v165, v233
	v_mul_f32_e32 v230, v230, v166
	v_mul_f32_e32 v231, v231, v167
	v_mul_f32_e32 v232, v232, v168
	v_mul_f32_e32 v233, v233, v169
	v_cvt_pk_bf16_f32 v208, v230, v231
	v_cvt_pk_bf16_f32 v209, v232, v233
	v_pk_mul_f32 v[76:77], v[76:77], v[204:205] op_sel_hi:[1,0]
	v_pk_mul_f32 v[78:79], v[78:79], v[204:205] op_sel_hi:[1,0]
	v_pk_mul_f32 v[72:73], v[72:73], v[204:205] op_sel_hi:[1,0]
	v_pk_mul_f32 v[74:75], v[74:75], v[204:205] op_sel_hi:[1,0]
	v_pk_mul_f32 v[162:163], v[76:77], v[138:139]
	v_pk_mul_f32 v[164:165], v[78:79], v[140:141]
	v_pk_mul_f32 v[166:167], v[72:73], v[150:151]
	v_pk_mul_f32 v[168:169], v[74:75], v[152:153]
	v_fmac_f32_dpp v162, v76, v134 row_shr:1 row_mask:0xf bank_mask:0xf
	v_fmac_f32_dpp v163, v77, v135 row_shr:1 row_mask:0xf bank_mask:0xf
	v_fmac_f32_dpp v164, v78, v136 row_shr:1 row_mask:0xf bank_mask:0xf
	v_fmac_f32_dpp v165, v79, v137 row_shr:1 row_mask:0xf bank_mask:0xf
	v_fmac_f32_dpp v166, v72, v146 row_shr:1 row_mask:0xf bank_mask:0xf
	v_fmac_f32_dpp v167, v73, v147 row_shr:1 row_mask:0xf bank_mask:0xf
	v_fmac_f32_dpp v168, v74, v148 row_shr:1 row_mask:0xf bank_mask:0xf
	v_fmac_f32_dpp v169, v75, v149 row_shr:1 row_mask:0xf bank_mask:0xf
	v_fmac_f32_dpp v162, v76, v130 row_shr:2 row_mask:0xf bank_mask:0xf
	v_fmac_f32_dpp v163, v77, v131 row_shr:2 row_mask:0xf bank_mask:0xf
	v_fmac_f32_dpp v164, v78, v132 row_shr:2 row_mask:0xf bank_mask:0xf
	v_fmac_f32_dpp v165, v79, v133 row_shr:2 row_mask:0xf bank_mask:0xf
	v_fmac_f32_dpp v166, v72, v142 row_shr:2 row_mask:0xf bank_mask:0xf
	v_fmac_f32_dpp v167, v73, v143 row_shr:2 row_mask:0xf bank_mask:0xf
	v_fmac_f32_dpp v168, v74, v144 row_shr:2 row_mask:0xf bank_mask:0xf
	v_fmac_f32_dpp v169, v75, v145 row_shr:2 row_mask:0xf bank_mask:0xf
	v_fmac_f32_dpp v162, v84, v134 row_shl:15 row_mask:0xf bank_mask:0xf
	v_fmac_f32_dpp v163, v85, v135 row_shl:15 row_mask:0xf bank_mask:0xf
	v_fmac_f32_dpp v164, v86, v136 row_shl:15 row_mask:0xf bank_mask:0xf
	v_fmac_f32_dpp v165, v87, v137 row_shl:15 row_mask:0xf bank_mask:0xf
	v_fmac_f32_dpp v166, v80, v146 row_shl:15 row_mask:0xf bank_mask:0xf
	v_fmac_f32_dpp v167, v81, v147 row_shl:15 row_mask:0xf bank_mask:0xf
	v_fmac_f32_dpp v168, v82, v148 row_shl:15 row_mask:0xf bank_mask:0xf
	v_fmac_f32_dpp v169, v83, v149 row_shl:15 row_mask:0xf bank_mask:0xf
	v_fmac_f32_dpp v162, v84, v130 row_shl:14 row_mask:0xf bank_mask:0xf
; __device__ __forceinline__ unsigned cvt_pk_bf16(float lo, float hi) { unsigned r; asm volatile("v_cvt_pk_bf16_f32 %0, %1, %2" : "=v"(r) : "v"(lo), "v"(hi)); return r; }
;     static __device__ __forceinline__ float dpp_shr1(float old, float src) { return __builtin_bit_cast(float, __builtin_amdgcn_update_dpp(__builtin_bit_cast(int, old), __builtin_bit_cast(int, src), 0x111, 0xf, 0xf, false)); }
;     static __device__ __forceinline__ float dpp_shr2(float old, float src) { return __builtin_bit_cast(float, __builtin_amdgcn_update_dpp(__builtin_bit_cast(int, old), __builtin_bit_cast(int, src), 0x112, 0xf, 0xf, false)); }
;     static __device__ __forceinline__ float dpp_ror1(float src) { return __builtin_bit_cast(float, __builtin_amdgcn_update_dpp(0, __builtin_bit_cast(int, src), 0x121, 0xf, 0xf, true)); }
;     static __device__ __forceinline__ float dpp_ror2(float src) { return __builtin_bit_cast(float, __builtin_amdgcn_update_dpp(0, __builtin_bit_cast(int, src), 0x122, 0xf, 0xf, true)); }
;     __device__ __forceinline__ void operator()(const f32x4 (&acc)[2][2][4][2], const Unit& u, int wr, int wc, int fr, int fq) const {
;     ...
;                 for (int m = 0; m < 4; ++m) {
;                     f32x4 uu[2];
; #pragma unroll
;                     for (int bj = 0; bj < 2; ++bj) { const f32x4 cur = acc[ai][bj][m][n] * rs[ai][m];
; #pragma unroll
;                         for (int q = 0; q < 4; ++q) { const float p1 = dpp_shr1(o1[bj][q], cur[q]), p2 = dpp_shr2(o2[bj][q], cur[q]);
;                             uu[bj][q] = w[bj][0][q] * p2 + w[bj][1][q] * p1 + w[bj][2][q] * cur[q];
;                             o1[bj][q] = dpp_ror1(cur[q]); o2[bj][q] = dpp_ror2(cur[q]); } }
;                     u32x2v o;
;                     { const float a0 = uu[0][0] * __builtin_amdgcn_rcpf(1.f + __expf(-uu[0][0])) * uu[1][0], a1 = uu[0][1] * __builtin_amdgcn_rcpf(1.f + __expf(-uu[0][1])) * uu[1][1];
;                       const float a2 = uu[0][2] * __builtin_amdgcn_rcpf(1.f + __expf(-uu[0][2])) * uu[1][2], a3 = uu[0][3] * __builtin_amdgcn_rcpf(1.f + __expf(-uu[0][3])) * uu[1][3];
;                       o.x = cvt_pk_bf16(a0, a1); o.y = cvt_pk_bf16(a2, a3); }
	v_fmac_f32_dpp v163, v85, v131 row_shl:14 row_mask:0xf bank_mask:0xf
	v_fmac_f32_dpp v164, v86, v132 row_shl:14 row_mask:0xf bank_mask:0xf
	v_fmac_f32_dpp v165, v87, v133 row_shl:14 row_mask:0xf bank_mask:0xf
	v_fmac_f32_dpp v166, v80, v142 row_shl:14 row_mask:0xf bank_mask:0xf
	v_fmac_f32_dpp v167, v81, v143 row_shl:14 row_mask:0xf bank_mask:0xf
	v_fmac_f32_dpp v168, v82, v144 row_shl:14 row_mask:0xf bank_mask:0xf
	v_fmac_f32_dpp v169, v83, v145 row_shl:14 row_mask:0xf bank_mask:0xf
	v_mul_f32_e32 v230, 0xbfb8aa3b, v162
	v_mul_f32_e32 v231, 0xbfb8aa3b, v163
	v_mul_f32_e32 v232, 0xbfb8aa3b, v164
	v_mul_f32_e32 v233, 0xbfb8aa3b, v165
	v_exp_f32_e32 v230, v230
	v_exp_f32_e32 v231, v231
	v_exp_f32_e32 v232, v232
	v_exp_f32_e32 v233, v233
	v_add_f32_e32 v230, 1.0, v230
	v_add_f32_e32 v231, 1.0, v231
	v_add_f32_e32 v232, 1.0, v232
	v_add_f32_e32 v233, 1.0, v233
	v_rcp_f32_e32 v230, v230
	v_rcp_f32_e32 v231, v231
	v_rcp_f32_e32 v232, v232
	v_rcp_f32_e32 v233, v233
	v_mul_f32_e32 v230, v162, v230
	v_mul_f32_e32 v231, v163, v231
	v_mul_f32_e32 v232, v164, v232
	v_mul_f32_e32 v233, v165, v233
	v_mul_f32_e32 v230, v230, v166
	v_mul_f32_e32 v231, v231, v167
	v_mul_f32_e32 v232, v232, v168
	v_mul_f32_e32 v233, v233, v169
	v_cvt_pk_bf16_f32 v200, v230, v231
	v_cvt_pk_bf16_f32 v201, v232, v233
	v_pk_mul_f32 v[68:69], v[68:69], v[196:197] op_sel_hi:[1,0]
	v_pk_mul_f32 v[70:71], v[70:71], v[196:197] op_sel_hi:[1,0]
	v_pk_mul_f32 v[64:65], v[64:65], v[196:197] op_sel_hi:[1,0]
	v_pk_mul_f32 v[66:67], v[66:67], v[196:197] op_sel_hi:[1,0]
	v_pk_mul_f32 v[162:163], v[68:69], v[138:139]
	v_pk_mul_f32 v[164:165], v[70:71], v[140:141]
	v_pk_mul_f32 v[166:167], v[64:65], v[150:151]
	v_pk_mul_f32 v[168:169], v[66:67], v[152:153]
	v_fmac_f32_dpp v162, v68, v134 row_shr:1 row_mask:0xf bank_mask:0xf
	v_fmac_f32_dpp v163, v69, v135 row_shr:1 row_mask:0xf bank_mask:0xf
	v_fmac_f32_dpp v164, v70, v136 row_shr:1 row_mask:0xf bank_mask:0xf
	v_fmac_f32_dpp v165, v71, v137 row_shr:1 row_mask:0xf bank_mask:0xf
	v_fmac_f32_dpp v166, v64, v146 row_shr:1 row_mask:0xf bank_mask:0xf
	v_fmac_f32_dpp v167, v65, v147 row_shr:1 row_mask:0xf bank_mask:0xf
	v_fmac_f32_dpp v168, v66, v148 row_shr:1 row_mask:0xf bank_mask:0xf
	v_fmac_f32_dpp v169, v67, v149 row_shr:1 row_mask:0xf bank_mask:0xf
	v_fmac_f32_dpp v162, v68, v130 row_shr:2 row_mask:0xf bank_mask:0xf
	v_fmac_f32_dpp v163, v69, v131 row_shr:2 row_mask:0xf bank_mask:0xf
	v_fmac_f32_dpp v164, v70, v132 row_shr:2 row_mask:0xf bank_mask:0xf
	v_fmac_f32_dpp v165, v71, v133 row_shr:2 row_mask:0xf bank_mask:0xf
	v_fmac_f32_dpp v166, v64, v142 row_shr:2 row_mask:0xf bank_mask:0xf
	v_fmac_f32_dpp v167, v65, v143 row_shr:2 row_mask:0xf bank_mask:0xf
	v_fmac_f32_dpp v168, v66, v144 row_shr:2 row_mask:0xf bank_mask:0xf
	v_fmac_f32_dpp v169, v67, v145 row_shr:2 row_mask:0xf bank_mask:0xf
	v_fmac_f32_dpp v162, v76, v134 row_shl:15 row_mask:0xf bank_mask:0xf
	v_fmac_f32_dpp v163, v77, v135 row_shl:15 row_mask:0xf bank_mask:0xf
	v_fmac_f32_dpp v164, v78, v136 row_shl:15 row_mask:0xf bank_mask:0xf
	v_fmac_f32_dpp v165, v79, v137 row_shl:15 row_mask:0xf bank_mask:0xf
	v_fmac_f32_dpp v166, v72, v146 row_shl:15 row_mask:0xf bank_mask:0xf
	v_fmac_f32_dpp v167, v73, v147 row_shl:15 row_mask:0xf bank_mask:0xf
	v_fmac_f32_dpp v168, v74, v148 row_shl:15 row_mask:0xf bank_mask:0xf
	v_fmac_f32_dpp v169, v75, v149 row_shl:15 row_mask:0xf bank_mask:0xf
	v_fmac_f32_dpp v162, v76, v130 row_shl:14 row_mask:0xf bank_mask:0xf
	v_fmac_f32_dpp v163, v77, v131 row_shl:14 row_mask:0xf bank_mask:0xf
	v_fmac_f32_dpp v164, v78, v132 row_shl:14 row_mask:0xf bank_mask:0xf
	v_fmac_f32_dpp v165, v79, v133 row_shl:14 row_mask:0xf bank_mask:0xf
	v_fmac_f32_dpp v166, v72, v142 row_shl:14 row_mask:0xf bank_mask:0xf
	v_fmac_f32_dpp v167, v73, v143 row_shl:14 row_mask:0xf bank_mask:0xf
	v_fmac_f32_dpp v168, v74, v144 row_shl:14 row_mask:0xf bank_mask:0xf
	v_fmac_f32_dpp v169, v75, v145 row_shl:14 row_mask:0xf bank_mask:0xf
	v_mul_f32_e32 v230, 0xbfb8aa3b, v162
	v_mul_f32_e32 v231, 0xbfb8aa3b, v163
	v_mul_f32_e32 v232, 0xbfb8aa3b, v164
	v_mul_f32_e32 v233, 0xbfb8aa3b, v165
	v_exp_f32_e32 v230, v230
	v_exp_f32_e32 v231, v231
	v_exp_f32_e32 v232, v232
	v_exp_f32_e32 v233, v233
	v_add_f32_e32 v230, 1.0, v230
	v_add_f32_e32 v231, 1.0, v231
	v_add_f32_e32 v232, 1.0, v232
	v_add_f32_e32 v233, 1.0, v233
	v_rcp_f32_e32 v230, v230
	v_rcp_f32_e32 v231, v231
	v_rcp_f32_e32 v232, v232
	v_rcp_f32_e32 v233, v233
	v_mul_f32_e32 v230, v162, v230
	v_mul_f32_e32 v231, v163, v231
	v_mul_f32_e32 v232, v164, v232
	v_mul_f32_e32 v233, v165, v233
	v_mul_f32_e32 v230, v230, v166
	v_mul_f32_e32 v231, v231, v167
	v_mul_f32_e32 v232, v232, v168
	v_mul_f32_e32 v233, v233, v169
	v_cvt_pk_bf16_f32 v248, v230, v231
	v_cvt_pk_bf16_f32 v249, v232, v233
	s_waitcnt lgkmcnt(0)
; __device__ __forceinline__ unsigned cvt_pk_bf16(float lo, float hi) { unsigned r; asm volatile("v_cvt_pk_bf16_f32 %0, %1, %2" : "=v"(r) : "v"(lo), "v"(hi)); return r; }
;     static __device__ __forceinline__ float dpp_shr1(float old, float src) { return __builtin_bit_cast(float, __builtin_amdgcn_update_dpp(__builtin_bit_cast(int, old), __builtin_bit_cast(int, src), 0x111, 0xf, 0xf, false)); }
;     static __device__ __forceinline__ float dpp_shr2(float old, float src) { return __builtin_bit_cast(float, __builtin_amdgcn_update_dpp(__builtin_bit_cast(int, old), __builtin_bit_cast(int, src), 0x112, 0xf, 0xf, false)); }
;     static __device__ __forceinline__ float dpp_ror1(float src) { return __builtin_bit_cast(float, __builtin_amdgcn_update_dpp(0, __builtin_bit_cast(int, src), 0x121, 0xf, 0xf, true)); }
;     static __device__ __forceinline__ float dpp_ror2(float src) { return __builtin_bit_cast(float, __builtin_amdgcn_update_dpp(0, __builtin_bit_cast(int, src), 0x122, 0xf, 0xf, true)); }
;     __device__ __forceinline__ void operator()(const f32x4 (&acc)[2][2][4][2], const Unit& u, int wr, int wc, int fr, int fq) const {
;     ...
;                 for (int m = 0; m < 4; ++m) {
;                     f32x4 uu[2];
; #pragma unroll
;                     for (int bj = 0; bj < 2; ++bj) { const f32x4 cur = acc[ai][bj][m][n] * rs[ai][m];
; #pragma unroll
;                         for (int q = 0; q < 4; ++q) { const float p1 = dpp_shr1(o1[bj][q], cur[q]), p2 = dpp_shr2(o2[bj][q], cur[q]);
;                             uu[bj][q] = w[bj][0][q] * p2 + w[bj][1][q] * p1 + w[bj][2][q] * cur[q];
;                             o1[bj][q] = dpp_ror1(cur[q]); o2[bj][q] = dpp_ror2(cur[q]); } }
;                     u32x2v o;
;                     { const float a0 = uu[0][0] * __builtin_amdgcn_rcpf(1.f + __expf(-uu[0][0])) * uu[1][0], a1 = uu[0][1] * __builtin_amdgcn_rcpf(1.f + __expf(-uu[0][1])) * uu[1][1];
;                       const float a2 = uu[0][2] * __builtin_amdgcn_rcpf(1.f + __expf(-uu[0][2])) * uu[1][2], a3 = uu[0][3] * __builtin_amdgcn_rcpf(1.f + __expf(-uu[0][3])) * uu[1][3];
;                       o.x = cvt_pk_bf16(a0, a1); o.y = cvt_pk_bf16(a2, a3); }
;                     *(u32x2v*)(ACT + (size_t)(row0 + ai * HALF + m * 16) * 5632 + u.pn * 128 + cidx + 4 * n) = o;
	v_pk_mul_f32 v[60:61], v[60:61], v[210:211] op_sel_hi:[1,0]
	v_pk_mul_f32 v[62:63], v[62:63], v[210:211] op_sel_hi:[1,0]
	v_pk_mul_f32 v[56:57], v[56:57], v[210:211] op_sel_hi:[1,0]
	v_pk_mul_f32 v[58:59], v[58:59], v[210:211] op_sel_hi:[1,0]
	v_pk_mul_f32 v[162:163], v[60:61], v[104:105]
	v_pk_mul_f32 v[164:165], v[62:63], v[106:107]
	v_pk_mul_f32 v[166:167], v[56:57], v[116:117]
	v_pk_mul_f32 v[168:169], v[58:59], v[118:119]
	v_fmac_f32_dpp v162, v60, v100 row_shr:1 row_mask:0xf bank_mask:0xf
	v_fmac_f32_dpp v163, v61, v101 row_shr:1 row_mask:0xf bank_mask:0xf
	v_fmac_f32_dpp v164, v62, v102 row_shr:1 row_mask:0xf bank_mask:0xf
	v_fmac_f32_dpp v165, v63, v103 row_shr:1 row_mask:0xf bank_mask:0xf
	v_fmac_f32_dpp v166, v56, v112 row_shr:1 row_mask:0xf bank_mask:0xf
	v_fmac_f32_dpp v167, v57, v113 row_shr:1 row_mask:0xf bank_mask:0xf
	v_fmac_f32_dpp v168, v58, v114 row_shr:1 row_mask:0xf bank_mask:0xf
	v_fmac_f32_dpp v169, v59, v115 row_shr:1 row_mask:0xf bank_mask:0xf
	v_fmac_f32_dpp v162, v60, v96 row_shr:2 row_mask:0xf bank_mask:0xf
	v_fmac_f32_dpp v163, v61, v97 row_shr:2 row_mask:0xf bank_mask:0xf
	v_fmac_f32_dpp v164, v62, v98 row_shr:2 row_mask:0xf bank_mask:0xf
	v_fmac_f32_dpp v165, v63, v99 row_shr:2 row_mask:0xf bank_mask:0xf
	v_fmac_f32_dpp v166, v56, v108 row_shr:2 row_mask:0xf bank_mask:0xf
	v_fmac_f32_dpp v167, v57, v109 row_shr:2 row_mask:0xf bank_mask:0xf
	v_fmac_f32_dpp v168, v58, v110 row_shr:2 row_mask:0xf bank_mask:0xf
	v_fmac_f32_dpp v169, v59, v111 row_shr:2 row_mask:0xf bank_mask:0xf
	v_fmac_f32_dpp v162, v154, v100 row_shl:15 row_mask:0xf bank_mask:0xf
	v_fmac_f32_dpp v163, v155, v101 row_shl:15 row_mask:0xf bank_mask:0xf
	v_fmac_f32_dpp v164, v156, v102 row_shl:15 row_mask:0xf bank_mask:0xf
	v_fmac_f32_dpp v165, v157, v103 row_shl:15 row_mask:0xf bank_mask:0xf
	v_fmac_f32_dpp v166, v158, v112 row_shl:15 row_mask:0xf bank_mask:0xf
	v_fmac_f32_dpp v167, v159, v113 row_shl:15 row_mask:0xf bank_mask:0xf
	v_fmac_f32_dpp v168, v160, v114 row_shl:15 row_mask:0xf bank_mask:0xf
	v_fmac_f32_dpp v169, v161, v115 row_shl:15 row_mask:0xf bank_mask:0xf
	v_fmac_f32_dpp v162, v154, v96 row_shl:14 row_mask:0xf bank_mask:0xf
	v_fmac_f32_dpp v163, v155, v97 row_shl:14 row_mask:0xf bank_mask:0xf
	v_fmac_f32_dpp v164, v156, v98 row_shl:14 row_mask:0xf bank_mask:0xf
	v_fmac_f32_dpp v165, v157, v99 row_shl:14 row_mask:0xf bank_mask:0xf
	v_fmac_f32_dpp v166, v158, v108 row_shl:14 row_mask:0xf bank_mask:0xf
	v_fmac_f32_dpp v167, v159, v109 row_shl:14 row_mask:0xf bank_mask:0xf
	v_fmac_f32_dpp v168, v160, v110 row_shl:14 row_mask:0xf bank_mask:0xf
	v_fmac_f32_dpp v169, v161, v111 row_shl:14 row_mask:0xf bank_mask:0xf
	v_mul_f32_e32 v230, 0xbfb8aa3b, v162
	v_mul_f32_e32 v231, 0xbfb8aa3b, v163
	v_mul_f32_e32 v232, 0xbfb8aa3b, v164
	v_mul_f32_e32 v233, 0xbfb8aa3b, v165
	v_exp_f32_e32 v230, v230
	v_exp_f32_e32 v231, v231
	v_exp_f32_e32 v232, v232
	v_exp_f32_e32 v233, v233
	v_add_f32_e32 v230, 1.0, v230
	v_add_f32_e32 v231, 1.0, v231
	v_add_f32_e32 v232, 1.0, v232
	v_add_f32_e32 v233, 1.0, v233
	v_rcp_f32_e32 v230, v230
	v_rcp_f32_e32 v231, v231
	v_rcp_f32_e32 v232, v232
	v_rcp_f32_e32 v233, v233
	v_mul_f32_e32 v230, v162, v230
	v_mul_f32_e32 v231, v163, v231
	v_mul_f32_e32 v232, v164, v232
	v_mul_f32_e32 v233, v165, v233
	v_mul_f32_e32 v230, v230, v166
	v_mul_f32_e32 v231, v231, v167
	v_mul_f32_e32 v232, v232, v168
	v_mul_f32_e32 v233, v233, v169
	v_mov_b32_e32 v64, v224
	v_mov_b32_e32 v65, v225
	v_cvt_pk_bf16_f32 v66, v230, v231
	v_cvt_pk_bf16_f32 v67, v232, v233
	global_store_dwordx4 v[246:247], v[64:67], off
	ds_read_b128 v[154:157], v197 offset:4112
	ds_read_b128 v[158:161], v197 offset:4624
	v_pk_mul_f32 v[52:53], v[52:53], v[214:215] op_sel_hi:[1,0]
	v_pk_mul_f32 v[54:55], v[54:55], v[214:215] op_sel_hi:[1,0]
	v_pk_mul_f32 v[48:49], v[48:49], v[214:215] op_sel_hi:[1,0]
	v_pk_mul_f32 v[50:51], v[50:51], v[214:215] op_sel_hi:[1,0]
	v_pk_mul_f32 v[162:163], v[52:53], v[104:105]
	v_pk_mul_f32 v[164:165], v[54:55], v[106:107]
	v_pk_mul_f32 v[166:167], v[48:49], v[116:117]
	v_pk_mul_f32 v[168:169], v[50:51], v[118:119]
	v_fmac_f32_dpp v162, v52, v100 row_shr:1 row_mask:0xf bank_mask:0xf
	v_fmac_f32_dpp v163, v53, v101 row_shr:1 row_mask:0xf bank_mask:0xf
	v_fmac_f32_dpp v164, v54, v102 row_shr:1 row_mask:0xf bank_mask:0xf
	v_fmac_f32_dpp v165, v55, v103 row_shr:1 row_mask:0xf bank_mask:0xf
	v_fmac_f32_dpp v166, v48, v112 row_shr:1 row_mask:0xf bank_mask:0xf
	v_fmac_f32_dpp v167, v49, v113 row_shr:1 row_mask:0xf bank_mask:0xf
	v_fmac_f32_dpp v168, v50, v114 row_shr:1 row_mask:0xf bank_mask:0xf
	v_fmac_f32_dpp v169, v51, v115 row_shr:1 row_mask:0xf bank_mask:0xf
	v_fmac_f32_dpp v162, v52, v96 row_shr:2 row_mask:0xf bank_mask:0xf
	v_fmac_f32_dpp v163, v53, v97 row_shr:2 row_mask:0xf bank_mask:0xf
	v_fmac_f32_dpp v164, v54, v98 row_shr:2 row_mask:0xf bank_mask:0xf
	v_fmac_f32_dpp v165, v55, v99 row_shr:2 row_mask:0xf bank_mask:0xf
	v_fmac_f32_dpp v166, v48, v108 row_shr:2 row_mask:0xf bank_mask:0xf
	v_fmac_f32_dpp v167, v49, v109 row_shr:2 row_mask:0xf bank_mask:0xf
	v_fmac_f32_dpp v168, v50, v110 row_shr:2 row_mask:0xf bank_mask:0xf
	v_fmac_f32_dpp v169, v51, v111 row_shr:2 row_mask:0xf bank_mask:0xf
	v_fmac_f32_dpp v162, v60, v100 row_shl:15 row_mask:0xf bank_mask:0xf
	v_fmac_f32_dpp v163, v61, v101 row_shl:15 row_mask:0xf bank_mask:0xf
	v_fmac_f32_dpp v164, v62, v102 row_shl:15 row_mask:0xf bank_mask:0xf
	v_fmac_f32_dpp v165, v63, v103 row_shl:15 row_mask:0xf bank_mask:0xf
	v_fmac_f32_dpp v166, v56, v112 row_shl:15 row_mask:0xf bank_mask:0xf
	v_fmac_f32_dpp v167, v57, v113 row_shl:15 row_mask:0xf bank_mask:0xf
; __device__ __forceinline__ unsigned cvt_pk_bf16(float lo, float hi) { unsigned r; asm volatile("v_cvt_pk_bf16_f32 %0, %1, %2" : "=v"(r) : "v"(lo), "v"(hi)); return r; }
;     static __device__ __forceinline__ float dpp_shr1(float old, float src) { return __builtin_bit_cast(float, __builtin_amdgcn_update_dpp(__builtin_bit_cast(int, old), __builtin_bit_cast(int, src), 0x111, 0xf, 0xf, false)); }
;     static __device__ __forceinline__ float dpp_shr2(float old, float src) { return __builtin_bit_cast(float, __builtin_amdgcn_update_dpp(__builtin_bit_cast(int, old), __builtin_bit_cast(int, src), 0x112, 0xf, 0xf, false)); }
;     static __device__ __forceinline__ float dpp_ror1(float src) { return __builtin_bit_cast(float, __builtin_amdgcn_update_dpp(0, __builtin_bit_cast(int, src), 0x121, 0xf, 0xf, true)); }
;     static __device__ __forceinline__ float dpp_ror2(float src) { return __builtin_bit_cast(float, __builtin_amdgcn_update_dpp(0, __builtin_bit_cast(int, src), 0x122, 0xf, 0xf, true)); }
;     __device__ __forceinline__ void operator()(const f32x4 (&acc)[2][2][4][2], const Unit& u, int wr, int wc, int fr, int fq) const {
;     ...
;                 for (int m = 0; m < 4; ++m) {
;                     f32x4 uu[2];
; #pragma unroll
;                     for (int bj = 0; bj < 2; ++bj) { const f32x4 cur = acc[ai][bj][m][n] * rs[ai][m];
; #pragma unroll
;                         for (int q = 0; q < 4; ++q) { const float p1 = dpp_shr1(o1[bj][q], cur[q]), p2 = dpp_shr2(o2[bj][q], cur[q]);
;                             uu[bj][q] = w[bj][0][q] * p2 + w[bj][1][q] * p1 + w[bj][2][q] * cur[q];
;                             o1[bj][q] = dpp_ror1(cur[q]); o2[bj][q] = dpp_ror2(cur[q]); } }
;                     u32x2v o;
;                     { const float a0 = uu[0][0] * __builtin_amdgcn_rcpf(1.f + __expf(-uu[0][0])) * uu[1][0], a1 = uu[0][1] * __builtin_amdgcn_rcpf(1.f + __expf(-uu[0][1])) * uu[1][1];
;                       const float a2 = uu[0][2] * __builtin_amdgcn_rcpf(1.f + __expf(-uu[0][2])) * uu[1][2], a3 = uu[0][3] * __builtin_amdgcn_rcpf(1.f + __expf(-uu[0][3])) * uu[1][3];
;                       o.x = cvt_pk_bf16(a0, a1); o.y = cvt_pk_bf16(a2, a3); }
;                     *(u32x2v*)(ACT + (size_t)(row0 + ai * HALF + m * 16) * 5632 + u.pn * 128 + cidx + 4 * n) = o;
	v_fmac_f32_dpp v168, v58, v114 row_shl:15 row_mask:0xf bank_mask:0xf
	v_fmac_f32_dpp v169, v59, v115 row_shl:15 row_mask:0xf bank_mask:0xf
	v_fmac_f32_dpp v162, v60, v96 row_shl:14 row_mask:0xf bank_mask:0xf
	v_fmac_f32_dpp v163, v61, v97 row_shl:14 row_mask:0xf bank_mask:0xf
	v_fmac_f32_dpp v164, v62, v98 row_shl:14 row_mask:0xf bank_mask:0xf
	v_fmac_f32_dpp v165, v63, v99 row_shl:14 row_mask:0xf bank_mask:0xf
	v_fmac_f32_dpp v166, v56, v108 row_shl:14 row_mask:0xf bank_mask:0xf
	v_fmac_f32_dpp v167, v57, v109 row_shl:14 row_mask:0xf bank_mask:0xf
	v_fmac_f32_dpp v168, v58, v110 row_shl:14 row_mask:0xf bank_mask:0xf
	v_fmac_f32_dpp v169, v59, v111 row_shl:14 row_mask:0xf bank_mask:0xf
	v_mul_f32_e32 v230, 0xbfb8aa3b, v162
	v_mul_f32_e32 v231, 0xbfb8aa3b, v163
	v_mul_f32_e32 v232, 0xbfb8aa3b, v164
	v_mul_f32_e32 v233, 0xbfb8aa3b, v165
	v_exp_f32_e32 v230, v230
	v_exp_f32_e32 v231, v231
	v_exp_f32_e32 v232, v232
	v_exp_f32_e32 v233, v233
	v_add_f32_e32 v230, 1.0, v230
	v_add_f32_e32 v231, 1.0, v231
	v_add_f32_e32 v232, 1.0, v232
	v_add_f32_e32 v233, 1.0, v233
	v_rcp_f32_e32 v230, v230
	v_rcp_f32_e32 v231, v231
	v_rcp_f32_e32 v232, v232
	v_rcp_f32_e32 v233, v233
	v_mul_f32_e32 v230, v162, v230
	v_mul_f32_e32 v231, v163, v231
	v_mul_f32_e32 v232, v164, v232
	v_mul_f32_e32 v233, v165, v233
	v_mul_f32_e32 v230, v230, v166
	v_mul_f32_e32 v231, v231, v167
	v_mul_f32_e32 v232, v232, v168
	v_mul_f32_e32 v233, v233, v169
	v_mov_b32_e32 v68, v226
	v_mov_b32_e32 v69, v227
	v_cvt_pk_bf16_f32 v70, v230, v231
	v_cvt_pk_bf16_f32 v71, v232, v233
	s_mov_b32 s8, 0x2c000
	v_lshl_add_u64 v[234:235], v[246:247], 0, s[8:9]
	global_store_dwordx4 v[234:235], v[68:71], off
	v_pk_mul_f32 v[44:45], v[44:45], v[218:219] op_sel_hi:[1,0]
	v_pk_mul_f32 v[46:47], v[46:47], v[218:219] op_sel_hi:[1,0]
	v_pk_mul_f32 v[40:41], v[40:41], v[218:219] op_sel_hi:[1,0]
	v_pk_mul_f32 v[42:43], v[42:43], v[218:219] op_sel_hi:[1,0]
	v_pk_mul_f32 v[162:163], v[44:45], v[104:105]
	v_pk_mul_f32 v[164:165], v[46:47], v[106:107]
	v_pk_mul_f32 v[166:167], v[40:41], v[116:117]
	v_pk_mul_f32 v[168:169], v[42:43], v[118:119]
	v_fmac_f32_dpp v162, v44, v100 row_shr:1 row_mask:0xf bank_mask:0xf
	v_fmac_f32_dpp v163, v45, v101 row_shr:1 row_mask:0xf bank_mask:0xf
	v_fmac_f32_dpp v164, v46, v102 row_shr:1 row_mask:0xf bank_mask:0xf
	v_fmac_f32_dpp v165, v47, v103 row_shr:1 row_mask:0xf bank_mask:0xf
	v_fmac_f32_dpp v166, v40, v112 row_shr:1 row_mask:0xf bank_mask:0xf
	v_fmac_f32_dpp v167, v41, v113 row_shr:1 row_mask:0xf bank_mask:0xf
	v_fmac_f32_dpp v168, v42, v114 row_shr:1 row_mask:0xf bank_mask:0xf
	v_fmac_f32_dpp v169, v43, v115 row_shr:1 row_mask:0xf bank_mask:0xf
	v_fmac_f32_dpp v162, v44, v96 row_shr:2 row_mask:0xf bank_mask:0xf
	v_fmac_f32_dpp v163, v45, v97 row_shr:2 row_mask:0xf bank_mask:0xf
	v_fmac_f32_dpp v164, v46, v98 row_shr:2 row_mask:0xf bank_mask:0xf
	v_fmac_f32_dpp v165, v47, v99 row_shr:2 row_mask:0xf bank_mask:0xf
	v_fmac_f32_dpp v166, v40, v108 row_shr:2 row_mask:0xf bank_mask:0xf
	v_fmac_f32_dpp v167, v41, v109 row_shr:2 row_mask:0xf bank_mask:0xf
	v_fmac_f32_dpp v168, v42, v110 row_shr:2 row_mask:0xf bank_mask:0xf
	v_fmac_f32_dpp v169, v43, v111 row_shr:2 row_mask:0xf bank_mask:0xf
	v_fmac_f32_dpp v162, v52, v100 row_shl:15 row_mask:0xf bank_mask:0xf
	v_fmac_f32_dpp v163, v53, v101 row_shl:15 row_mask:0xf bank_mask:0xf
	v_fmac_f32_dpp v164, v54, v102 row_shl:15 row_mask:0xf bank_mask:0xf
	v_fmac_f32_dpp v165, v55, v103 row_shl:15 row_mask:0xf bank_mask:0xf
	v_fmac_f32_dpp v166, v48, v112 row_shl:15 row_mask:0xf bank_mask:0xf
	v_fmac_f32_dpp v167, v49, v113 row_shl:15 row_mask:0xf bank_mask:0xf
	v_fmac_f32_dpp v168, v50, v114 row_shl:15 row_mask:0xf bank_mask:0xf
	v_fmac_f32_dpp v169, v51, v115 row_shl:15 row_mask:0xf bank_mask:0xf
	v_fmac_f32_dpp v162, v52, v96 row_shl:14 row_mask:0xf bank_mask:0xf
	v_fmac_f32_dpp v163, v53, v97 row_shl:14 row_mask:0xf bank_mask:0xf
	v_fmac_f32_dpp v164, v54, v98 row_shl:14 row_mask:0xf bank_mask:0xf
	v_fmac_f32_dpp v165, v55, v99 row_shl:14 row_mask:0xf bank_mask:0xf
	v_fmac_f32_dpp v166, v48, v108 row_shl:14 row_mask:0xf bank_mask:0xf
	v_fmac_f32_dpp v167, v49, v109 row_shl:14 row_mask:0xf bank_mask:0xf
	v_fmac_f32_dpp v168, v50, v110 row_shl:14 row_mask:0xf bank_mask:0xf
	v_fmac_f32_dpp v169, v51, v111 row_shl:14 row_mask:0xf bank_mask:0xf
	v_mul_f32_e32 v230, 0xbfb8aa3b, v162
	v_mul_f32_e32 v231, 0xbfb8aa3b, v163
	v_mul_f32_e32 v232, 0xbfb8aa3b, v164
	v_mul_f32_e32 v233, 0xbfb8aa3b, v165
	v_exp_f32_e32 v230, v230
	v_exp_f32_e32 v231, v231
	v_exp_f32_e32 v232, v232
	v_exp_f32_e32 v233, v233
	v_add_f32_e32 v230, 1.0, v230
	v_add_f32_e32 v231, 1.0, v231
	v_add_f32_e32 v232, 1.0, v232
	v_add_f32_e32 v233, 1.0, v233
	v_rcp_f32_e32 v230, v230
	v_rcp_f32_e32 v231, v231
	v_rcp_f32_e32 v232, v232
	v_rcp_f32_e32 v233, v233
	v_mul_f32_e32 v230, v162, v230
	v_mul_f32_e32 v231, v163, v231
	v_mul_f32_e32 v232, v164, v232
	v_mul_f32_e32 v233, v165, v233
	v_mul_f32_e32 v230, v230, v166
	v_mul_f32_e32 v231, v231, v167
	v_mul_f32_e32 v232, v232, v168
	v_mul_f32_e32 v233, v233, v169
	v_mov_b32_e32 v72, v216
	v_mov_b32_e32 v73, v217
	v_cvt_pk_bf16_f32 v74, v230, v231
	v_cvt_pk_bf16_f32 v75, v232, v233
	s_mov_b32 s8, 0x58000
	v_lshl_add_u64 v[234:235], v[246:247], 0, s[8:9]
	global_store_dwordx4 v[234:235], v[72:75], off
	v_pk_mul_f32 v[36:37], v[36:37], v[194:195] op_sel_hi:[1,0]
	v_pk_mul_f32 v[38:39], v[38:39], v[194:195] op_sel_hi:[1,0]
	v_pk_mul_f32 v[32:33], v[32:33], v[194:195] op_sel_hi:[1,0]
	v_pk_mul_f32 v[34:35], v[34:35], v[194:195] op_sel_hi:[1,0]
	v_pk_mul_f32 v[162:163], v[36:37], v[104:105]
	v_pk_mul_f32 v[164:165], v[38:39], v[106:107]
; __device__ __forceinline__ unsigned cvt_pk_bf16(float lo, float hi) { unsigned r; asm volatile("v_cvt_pk_bf16_f32 %0, %1, %2" : "=v"(r) : "v"(lo), "v"(hi)); return r; }
;     static __device__ __forceinline__ float dpp_shr1(float old, float src) { return __builtin_bit_cast(float, __builtin_amdgcn_update_dpp(__builtin_bit_cast(int, old), __builtin_bit_cast(int, src), 0x111, 0xf, 0xf, false)); }
;     static __device__ __forceinline__ float dpp_shr2(float old, float src) { return __builtin_bit_cast(float, __builtin_amdgcn_update_dpp(__builtin_bit_cast(int, old), __builtin_bit_cast(int, src), 0x112, 0xf, 0xf, false)); }
;     static __device__ __forceinline__ float dpp_ror1(float src) { return __builtin_bit_cast(float, __builtin_amdgcn_update_dpp(0, __builtin_bit_cast(int, src), 0x121, 0xf, 0xf, true)); }
;     static __device__ __forceinline__ float dpp_ror2(float src) { return __builtin_bit_cast(float, __builtin_amdgcn_update_dpp(0, __builtin_bit_cast(int, src), 0x122, 0xf, 0xf, true)); }
;     __device__ __forceinline__ void operator()(const f32x4 (&acc)[2][2][4][2], const Unit& u, int wr, int wc, int fr, int fq) const {
;     ...
;                 for (int m = 0; m < 4; ++m) {
;                     f32x4 uu[2];
; #pragma unroll
;                     for (int bj = 0; bj < 2; ++bj) { const f32x4 cur = acc[ai][bj][m][n] * rs[ai][m];
; #pragma unroll
;                         for (int q = 0; q < 4; ++q) { const float p1 = dpp_shr1(o1[bj][q], cur[q]), p2 = dpp_shr2(o2[bj][q], cur[q]);
;                             uu[bj][q] = w[bj][0][q] * p2 + w[bj][1][q] * p1 + w[bj][2][q] * cur[q];
;                             o1[bj][q] = dpp_ror1(cur[q]); o2[bj][q] = dpp_ror2(cur[q]); } }
;                     u32x2v o;
;                     { const float a0 = uu[0][0] * __builtin_amdgcn_rcpf(1.f + __expf(-uu[0][0])) * uu[1][0], a1 = uu[0][1] * __builtin_amdgcn_rcpf(1.f + __expf(-uu[0][1])) * uu[1][1];
;                       const float a2 = uu[0][2] * __builtin_amdgcn_rcpf(1.f + __expf(-uu[0][2])) * uu[1][2], a3 = uu[0][3] * __builtin_amdgcn_rcpf(1.f + __expf(-uu[0][3])) * uu[1][3];
;                       o.x = cvt_pk_bf16(a0, a1); o.y = cvt_pk_bf16(a2, a3); }
;                     *(u32x2v*)(ACT + (size_t)(row0 + ai * HALF + m * 16) * 5632 + u.pn * 128 + cidx + 4 * n) = o;
	v_pk_mul_f32 v[166:167], v[32:33], v[116:117]
	v_pk_mul_f32 v[168:169], v[34:35], v[118:119]
	v_fmac_f32_dpp v162, v36, v100 row_shr:1 row_mask:0xf bank_mask:0xf
	v_fmac_f32_dpp v163, v37, v101 row_shr:1 row_mask:0xf bank_mask:0xf
	v_fmac_f32_dpp v164, v38, v102 row_shr:1 row_mask:0xf bank_mask:0xf
	v_fmac_f32_dpp v165, v39, v103 row_shr:1 row_mask:0xf bank_mask:0xf
	v_fmac_f32_dpp v166, v32, v112 row_shr:1 row_mask:0xf bank_mask:0xf
	v_fmac_f32_dpp v167, v33, v113 row_shr:1 row_mask:0xf bank_mask:0xf
	v_fmac_f32_dpp v168, v34, v114 row_shr:1 row_mask:0xf bank_mask:0xf
	v_fmac_f32_dpp v169, v35, v115 row_shr:1 row_mask:0xf bank_mask:0xf
	v_fmac_f32_dpp v162, v36, v96 row_shr:2 row_mask:0xf bank_mask:0xf
	v_fmac_f32_dpp v163, v37, v97 row_shr:2 row_mask:0xf bank_mask:0xf
	v_fmac_f32_dpp v164, v38, v98 row_shr:2 row_mask:0xf bank_mask:0xf
	v_fmac_f32_dpp v165, v39, v99 row_shr:2 row_mask:0xf bank_mask:0xf
	v_fmac_f32_dpp v166, v32, v108 row_shr:2 row_mask:0xf bank_mask:0xf
	v_fmac_f32_dpp v167, v33, v109 row_shr:2 row_mask:0xf bank_mask:0xf
	v_fmac_f32_dpp v168, v34, v110 row_shr:2 row_mask:0xf bank_mask:0xf
	v_fmac_f32_dpp v169, v35, v111 row_shr:2 row_mask:0xf bank_mask:0xf
	v_fmac_f32_dpp v162, v44, v100 row_shl:15 row_mask:0xf bank_mask:0xf
	v_fmac_f32_dpp v163, v45, v101 row_shl:15 row_mask:0xf bank_mask:0xf
	v_fmac_f32_dpp v164, v46, v102 row_shl:15 row_mask:0xf bank_mask:0xf
	v_fmac_f32_dpp v165, v47, v103 row_shl:15 row_mask:0xf bank_mask:0xf
	v_fmac_f32_dpp v166, v40, v112 row_shl:15 row_mask:0xf bank_mask:0xf
	v_fmac_f32_dpp v167, v41, v113 row_shl:15 row_mask:0xf bank_mask:0xf
	v_fmac_f32_dpp v168, v42, v114 row_shl:15 row_mask:0xf bank_mask:0xf
	v_fmac_f32_dpp v169, v43, v115 row_shl:15 row_mask:0xf bank_mask:0xf
	v_fmac_f32_dpp v162, v44, v96 row_shl:14 row_mask:0xf bank_mask:0xf
	v_fmac_f32_dpp v163, v45, v97 row_shl:14 row_mask:0xf bank_mask:0xf
	v_fmac_f32_dpp v164, v46, v98 row_shl:14 row_mask:0xf bank_mask:0xf
	v_fmac_f32_dpp v165, v47, v99 row_shl:14 row_mask:0xf bank_mask:0xf
	v_fmac_f32_dpp v166, v40, v108 row_shl:14 row_mask:0xf bank_mask:0xf
	v_fmac_f32_dpp v167, v41, v109 row_shl:14 row_mask:0xf bank_mask:0xf
	v_fmac_f32_dpp v168, v42, v110 row_shl:14 row_mask:0xf bank_mask:0xf
	v_fmac_f32_dpp v169, v43, v111 row_shl:14 row_mask:0xf bank_mask:0xf
	v_mul_f32_e32 v230, 0xbfb8aa3b, v162
	v_mul_f32_e32 v231, 0xbfb8aa3b, v163
	v_mul_f32_e32 v232, 0xbfb8aa3b, v164
	v_mul_f32_e32 v233, 0xbfb8aa3b, v165
	v_exp_f32_e32 v230, v230
	v_exp_f32_e32 v231, v231
	v_exp_f32_e32 v232, v232
	v_exp_f32_e32 v233, v233
	v_add_f32_e32 v230, 1.0, v230
	v_add_f32_e32 v231, 1.0, v231
	v_add_f32_e32 v232, 1.0, v232
	v_add_f32_e32 v233, 1.0, v233
	v_rcp_f32_e32 v230, v230
	v_rcp_f32_e32 v231, v231
	v_rcp_f32_e32 v232, v232
	v_rcp_f32_e32 v233, v233
	v_mul_f32_e32 v230, v162, v230
	v_mul_f32_e32 v231, v163, v231
	v_mul_f32_e32 v232, v164, v232
	v_mul_f32_e32 v233, v165, v233
	v_mul_f32_e32 v230, v230, v166
	v_mul_f32_e32 v231, v231, v167
	v_mul_f32_e32 v232, v232, v168
	v_mul_f32_e32 v233, v233, v169
	v_mov_b32_e32 v76, v220
	v_mov_b32_e32 v77, v221
	v_cvt_pk_bf16_f32 v78, v230, v231
	v_cvt_pk_bf16_f32 v79, v232, v233
	s_mov_b32 s8, 0x84000
	v_lshl_add_u64 v[234:235], v[246:247], 0, s[8:9]
	global_store_dwordx4 v[234:235], v[76:79], off
	s_waitcnt lgkmcnt(0)
	v_pk_mul_f32 v[28:29], v[28:29], v[198:199] op_sel_hi:[1,0]
	v_pk_mul_f32 v[30:31], v[30:31], v[198:199] op_sel_hi:[1,0]
	v_pk_mul_f32 v[24:25], v[24:25], v[198:199] op_sel_hi:[1,0]
	v_pk_mul_f32 v[26:27], v[26:27], v[198:199] op_sel_hi:[1,0]
	v_pk_mul_f32 v[162:163], v[28:29], v[104:105]
	v_pk_mul_f32 v[164:165], v[30:31], v[106:107]
	v_pk_mul_f32 v[166:167], v[24:25], v[116:117]
	v_pk_mul_f32 v[168:169], v[26:27], v[118:119]
	v_fmac_f32_dpp v162, v28, v100 row_shr:1 row_mask:0xf bank_mask:0xf
	v_fmac_f32_dpp v163, v29, v101 row_shr:1 row_mask:0xf bank_mask:0xf
	v_fmac_f32_dpp v164, v30, v102 row_shr:1 row_mask:0xf bank_mask:0xf
	v_fmac_f32_dpp v165, v31, v103 row_shr:1 row_mask:0xf bank_mask:0xf
	v_fmac_f32_dpp v166, v24, v112 row_shr:1 row_mask:0xf bank_mask:0xf
	v_fmac_f32_dpp v167, v25, v113 row_shr:1 row_mask:0xf bank_mask:0xf
	v_fmac_f32_dpp v168, v26, v114 row_shr:1 row_mask:0xf bank_mask:0xf
	v_fmac_f32_dpp v169, v27, v115 row_shr:1 row_mask:0xf bank_mask:0xf
	v_fmac_f32_dpp v162, v28, v96 row_shr:2 row_mask:0xf bank_mask:0xf
	v_fmac_f32_dpp v163, v29, v97 row_shr:2 row_mask:0xf bank_mask:0xf
	v_fmac_f32_dpp v164, v30, v98 row_shr:2 row_mask:0xf bank_mask:0xf
	v_fmac_f32_dpp v165, v31, v99 row_shr:2 row_mask:0xf bank_mask:0xf
	v_fmac_f32_dpp v166, v24, v108 row_shr:2 row_mask:0xf bank_mask:0xf
	v_fmac_f32_dpp v167, v25, v109 row_shr:2 row_mask:0xf bank_mask:0xf
	v_fmac_f32_dpp v168, v26, v110 row_shr:2 row_mask:0xf bank_mask:0xf
	v_fmac_f32_dpp v169, v27, v111 row_shr:2 row_mask:0xf bank_mask:0xf
	v_fmac_f32_dpp v162, v154, v100 row_shl:15 row_mask:0xf bank_mask:0xf
	v_fmac_f32_dpp v163, v155, v101 row_shl:15 row_mask:0xf bank_mask:0xf
	v_fmac_f32_dpp v164, v156, v102 row_shl:15 row_mask:0xf bank_mask:0xf
	v_fmac_f32_dpp v165, v157, v103 row_shl:15 row_mask:0xf bank_mask:0xf
	v_fmac_f32_dpp v166, v158, v112 row_shl:15 row_mask:0xf bank_mask:0xf
	v_fmac_f32_dpp v167, v159, v113 row_shl:15 row_mask:0xf bank_mask:0xf
	v_fmac_f32_dpp v168, v160, v114 row_shl:15 row_mask:0xf bank_mask:0xf
	v_fmac_f32_dpp v169, v161, v115 row_shl:15 row_mask:0xf bank_mask:0xf
	v_fmac_f32_dpp v162, v154, v96 row_shl:14 row_mask:0xf bank_mask:0xf
	v_fmac_f32_dpp v163, v155, v97 row_shl:14 row_mask:0xf bank_mask:0xf
	v_fmac_f32_dpp v164, v156, v98 row_shl:14 row_mask:0xf bank_mask:0xf
; __device__ __forceinline__ unsigned cvt_pk_bf16(float lo, float hi) { unsigned r; asm volatile("v_cvt_pk_bf16_f32 %0, %1, %2" : "=v"(r) : "v"(lo), "v"(hi)); return r; }
;     static __device__ __forceinline__ float dpp_shr1(float old, float src) { return __builtin_bit_cast(float, __builtin_amdgcn_update_dpp(__builtin_bit_cast(int, old), __builtin_bit_cast(int, src), 0x111, 0xf, 0xf, false)); }
;     static __device__ __forceinline__ float dpp_shr2(float old, float src) { return __builtin_bit_cast(float, __builtin_amdgcn_update_dpp(__builtin_bit_cast(int, old), __builtin_bit_cast(int, src), 0x112, 0xf, 0xf, false)); }
;     static __device__ __forceinline__ float dpp_ror1(float src) { return __builtin_bit_cast(float, __builtin_amdgcn_update_dpp(0, __builtin_bit_cast(int, src), 0x121, 0xf, 0xf, true)); }
;     static __device__ __forceinline__ float dpp_ror2(float src) { return __builtin_bit_cast(float, __builtin_amdgcn_update_dpp(0, __builtin_bit_cast(int, src), 0x122, 0xf, 0xf, true)); }
;     __device__ __forceinline__ void operator()(const f32x4 (&acc)[2][2][4][2], const Unit& u, int wr, int wc, int fr, int fq) const {
;     ...
;                 for (int m = 0; m < 4; ++m) {
;                     f32x4 uu[2];
; #pragma unroll
;                     for (int bj = 0; bj < 2; ++bj) { const f32x4 cur = acc[ai][bj][m][n] * rs[ai][m];
; #pragma unroll
;                         for (int q = 0; q < 4; ++q) { const float p1 = dpp_shr1(o1[bj][q], cur[q]), p2 = dpp_shr2(o2[bj][q], cur[q]);
;                             uu[bj][q] = w[bj][0][q] * p2 + w[bj][1][q] * p1 + w[bj][2][q] * cur[q];
;                             o1[bj][q] = dpp_ror1(cur[q]); o2[bj][q] = dpp_ror2(cur[q]); } }
;                     u32x2v o;
;                     { const float a0 = uu[0][0] * __builtin_amdgcn_rcpf(1.f + __expf(-uu[0][0])) * uu[1][0], a1 = uu[0][1] * __builtin_amdgcn_rcpf(1.f + __expf(-uu[0][1])) * uu[1][1];
;                       const float a2 = uu[0][2] * __builtin_amdgcn_rcpf(1.f + __expf(-uu[0][2])) * uu[1][2], a3 = uu[0][3] * __builtin_amdgcn_rcpf(1.f + __expf(-uu[0][3])) * uu[1][3];
;                       o.x = cvt_pk_bf16(a0, a1); o.y = cvt_pk_bf16(a2, a3); }
;                     *(u32x2v*)(ACT + (size_t)(row0 + ai * HALF + m * 16) * 5632 + u.pn * 128 + cidx + 4 * n) = o;
	v_fmac_f32_dpp v165, v157, v99 row_shl:14 row_mask:0xf bank_mask:0xf
	v_fmac_f32_dpp v166, v158, v108 row_shl:14 row_mask:0xf bank_mask:0xf
	v_fmac_f32_dpp v167, v159, v109 row_shl:14 row_mask:0xf bank_mask:0xf
	v_fmac_f32_dpp v168, v160, v110 row_shl:14 row_mask:0xf bank_mask:0xf
	v_fmac_f32_dpp v169, v161, v111 row_shl:14 row_mask:0xf bank_mask:0xf
	v_mul_f32_e32 v230, 0xbfb8aa3b, v162
	v_mul_f32_e32 v231, 0xbfb8aa3b, v163
	v_mul_f32_e32 v232, 0xbfb8aa3b, v164
	v_mul_f32_e32 v233, 0xbfb8aa3b, v165
	v_exp_f32_e32 v230, v230
	v_exp_f32_e32 v231, v231
	v_exp_f32_e32 v232, v232
	v_exp_f32_e32 v233, v233
	v_add_f32_e32 v230, 1.0, v230
	v_add_f32_e32 v231, 1.0, v231
	v_add_f32_e32 v232, 1.0, v232
	v_add_f32_e32 v233, 1.0, v233
	v_rcp_f32_e32 v230, v230
	v_rcp_f32_e32 v231, v231
	v_rcp_f32_e32 v232, v232
	v_rcp_f32_e32 v233, v233
	v_mul_f32_e32 v230, v162, v230
	v_mul_f32_e32 v231, v163, v231
	v_mul_f32_e32 v232, v164, v232
	v_mul_f32_e32 v233, v165, v233
	v_mul_f32_e32 v230, v230, v166
	v_mul_f32_e32 v231, v231, v167
	v_mul_f32_e32 v232, v232, v168
	v_mul_f32_e32 v233, v233, v169
	v_mov_b32_e32 v80, v212
	v_mov_b32_e32 v81, v213
	v_cvt_pk_bf16_f32 v82, v230, v231
	v_cvt_pk_bf16_f32 v83, v232, v233
	s_mov_b32 s8, 0x160000
	v_lshl_add_u64 v[234:235], v[246:247], 0, s[8:9]
	global_store_dwordx4 v[234:235], v[80:83], off
	v_pk_mul_f32 v[20:21], v[20:21], v[202:203] op_sel_hi:[1,0]
	v_pk_mul_f32 v[22:23], v[22:23], v[202:203] op_sel_hi:[1,0]
	v_pk_mul_f32 v[16:17], v[16:17], v[202:203] op_sel_hi:[1,0]
	v_pk_mul_f32 v[18:19], v[18:19], v[202:203] op_sel_hi:[1,0]
	v_pk_mul_f32 v[162:163], v[20:21], v[104:105]
	v_pk_mul_f32 v[164:165], v[22:23], v[106:107]
	v_pk_mul_f32 v[166:167], v[16:17], v[116:117]
	v_pk_mul_f32 v[168:169], v[18:19], v[118:119]
	v_fmac_f32_dpp v162, v20, v100 row_shr:1 row_mask:0xf bank_mask:0xf
	v_fmac_f32_dpp v163, v21, v101 row_shr:1 row_mask:0xf bank_mask:0xf
	v_fmac_f32_dpp v164, v22, v102 row_shr:1 row_mask:0xf bank_mask:0xf
	v_fmac_f32_dpp v165, v23, v103 row_shr:1 row_mask:0xf bank_mask:0xf
	v_fmac_f32_dpp v166, v16, v112 row_shr:1 row_mask:0xf bank_mask:0xf
	v_fmac_f32_dpp v167, v17, v113 row_shr:1 row_mask:0xf bank_mask:0xf
	v_fmac_f32_dpp v168, v18, v114 row_shr:1 row_mask:0xf bank_mask:0xf
	v_fmac_f32_dpp v169, v19, v115 row_shr:1 row_mask:0xf bank_mask:0xf
	v_fmac_f32_dpp v162, v20, v96 row_shr:2 row_mask:0xf bank_mask:0xf
	v_fmac_f32_dpp v163, v21, v97 row_shr:2 row_mask:0xf bank_mask:0xf
	v_fmac_f32_dpp v164, v22, v98 row_shr:2 row_mask:0xf bank_mask:0xf
	v_fmac_f32_dpp v165, v23, v99 row_shr:2 row_mask:0xf bank_mask:0xf
	v_fmac_f32_dpp v166, v16, v108 row_shr:2 row_mask:0xf bank_mask:0xf
	v_fmac_f32_dpp v167, v17, v109 row_shr:2 row_mask:0xf bank_mask:0xf
	v_fmac_f32_dpp v168, v18, v110 row_shr:2 row_mask:0xf bank_mask:0xf
	v_fmac_f32_dpp v169, v19, v111 row_shr:2 row_mask:0xf bank_mask:0xf
	v_fmac_f32_dpp v162, v28, v100 row_shl:15 row_mask:0xf bank_mask:0xf
	v_fmac_f32_dpp v163, v29, v101 row_shl:15 row_mask:0xf bank_mask:0xf
	v_fmac_f32_dpp v164, v30, v102 row_shl:15 row_mask:0xf bank_mask:0xf
	v_fmac_f32_dpp v165, v31, v103 row_shl:15 row_mask:0xf bank_mask:0xf
	v_fmac_f32_dpp v166, v24, v112 row_shl:15 row_mask:0xf bank_mask:0xf
	v_fmac_f32_dpp v167, v25, v113 row_shl:15 row_mask:0xf bank_mask:0xf
	v_fmac_f32_dpp v168, v26, v114 row_shl:15 row_mask:0xf bank_mask:0xf
	v_fmac_f32_dpp v169, v27, v115 row_shl:15 row_mask:0xf bank_mask:0xf
	v_fmac_f32_dpp v162, v28, v96 row_shl:14 row_mask:0xf bank_mask:0xf
	v_fmac_f32_dpp v163, v29, v97 row_shl:14 row_mask:0xf bank_mask:0xf
	v_fmac_f32_dpp v164, v30, v98 row_shl:14 row_mask:0xf bank_mask:0xf
	v_fmac_f32_dpp v165, v31, v99 row_shl:14 row_mask:0xf bank_mask:0xf
	v_fmac_f32_dpp v166, v24, v108 row_shl:14 row_mask:0xf bank_mask:0xf
	v_fmac_f32_dpp v167, v25, v109 row_shl:14 row_mask:0xf bank_mask:0xf
	v_fmac_f32_dpp v168, v26, v110 row_shl:14 row_mask:0xf bank_mask:0xf
	v_fmac_f32_dpp v169, v27, v111 row_shl:14 row_mask:0xf bank_mask:0xf
	v_mul_f32_e32 v230, 0xbfb8aa3b, v162
	v_mul_f32_e32 v231, 0xbfb8aa3b, v163
	v_mul_f32_e32 v232, 0xbfb8aa3b, v164
	v_mul_f32_e32 v233, 0xbfb8aa3b, v165
	v_exp_f32_e32 v230, v230
	v_exp_f32_e32 v231, v231
	v_exp_f32_e32 v232, v232
	v_exp_f32_e32 v233, v233
	v_add_f32_e32 v230, 1.0, v230
	v_add_f32_e32 v231, 1.0, v231
	v_add_f32_e32 v232, 1.0, v232
	v_add_f32_e32 v233, 1.0, v233
	v_rcp_f32_e32 v230, v230
	v_rcp_f32_e32 v231, v231
	v_rcp_f32_e32 v232, v232
	v_rcp_f32_e32 v233, v233
	v_mul_f32_e32 v230, v162, v230
	v_mul_f32_e32 v231, v163, v231
	v_mul_f32_e32 v232, v164, v232
	v_mul_f32_e32 v233, v165, v233
	v_mul_f32_e32 v230, v230, v166
	v_mul_f32_e32 v231, v231, v167
	v_mul_f32_e32 v232, v232, v168
	v_mul_f32_e32 v233, v233, v169
	v_mov_b32_e32 v84, v208
	v_mov_b32_e32 v85, v209
	v_cvt_pk_bf16_f32 v86, v230, v231
	v_cvt_pk_bf16_f32 v87, v232, v233
	s_mov_b32 s8, 0x18c000
	v_lshl_add_u64 v[234:235], v[246:247], 0, s[8:9]
	global_store_dwordx4 v[234:235], v[84:87], off
	v_pk_mul_f32 v[12:13], v[12:13], v[204:205] op_sel_hi:[1,0]
	v_pk_mul_f32 v[14:15], v[14:15], v[204:205] op_sel_hi:[1,0]
	v_pk_mul_f32 v[8:9], v[8:9], v[204:205] op_sel_hi:[1,0]
	v_pk_mul_f32 v[10:11], v[10:11], v[204:205] op_sel_hi:[1,0]
	v_pk_mul_f32 v[162:163], v[12:13], v[104:105]
	v_pk_mul_f32 v[164:165], v[14:15], v[106:107]
	v_pk_mul_f32 v[166:167], v[8:9], v[116:117]
	v_pk_mul_f32 v[168:169], v[10:11], v[118:119]
	v_fmac_f32_dpp v162, v12, v100 row_shr:1 row_mask:0xf bank_mask:0xf
	v_fmac_f32_dpp v163, v13, v101 row_shr:1 row_mask:0xf bank_mask:0xf
	v_fmac_f32_dpp v164, v14, v102 row_shr:1 row_mask:0xf bank_mask:0xf
	v_fmac_f32_dpp v165, v15, v103 row_shr:1 row_mask:0xf bank_mask:0xf
; __device__ __forceinline__ unsigned cvt_pk_bf16(float lo, float hi) { unsigned r; asm volatile("v_cvt_pk_bf16_f32 %0, %1, %2" : "=v"(r) : "v"(lo), "v"(hi)); return r; }
;     static __device__ __forceinline__ float dpp_shr1(float old, float src) { return __builtin_bit_cast(float, __builtin_amdgcn_update_dpp(__builtin_bit_cast(int, old), __builtin_bit_cast(int, src), 0x111, 0xf, 0xf, false)); }
;     static __device__ __forceinline__ float dpp_shr2(float old, float src) { return __builtin_bit_cast(float, __builtin_amdgcn_update_dpp(__builtin_bit_cast(int, old), __builtin_bit_cast(int, src), 0x112, 0xf, 0xf, false)); }
;     static __device__ __forceinline__ float dpp_ror1(float src) { return __builtin_bit_cast(float, __builtin_amdgcn_update_dpp(0, __builtin_bit_cast(int, src), 0x121, 0xf, 0xf, true)); }
;     static __device__ __forceinline__ float dpp_ror2(float src) { return __builtin_bit_cast(float, __builtin_amdgcn_update_dpp(0, __builtin_bit_cast(int, src), 0x122, 0xf, 0xf, true)); }
;     __device__ __forceinline__ void operator()(const f32x4 (&acc)[2][2][4][2], const Unit& u, int wr, int wc, int fr, int fq) const {
;     ...
;                 for (int m = 0; m < 4; ++m) {
;                     f32x4 uu[2];
; #pragma unroll
;                     for (int bj = 0; bj < 2; ++bj) { const f32x4 cur = acc[ai][bj][m][n] * rs[ai][m];
; #pragma unroll
;                         for (int q = 0; q < 4; ++q) { const float p1 = dpp_shr1(o1[bj][q], cur[q]), p2 = dpp_shr2(o2[bj][q], cur[q]);
;                             uu[bj][q] = w[bj][0][q] * p2 + w[bj][1][q] * p1 + w[bj][2][q] * cur[q];
;                             o1[bj][q] = dpp_ror1(cur[q]); o2[bj][q] = dpp_ror2(cur[q]); } }
;                     u32x2v o;
;                     { const float a0 = uu[0][0] * __builtin_amdgcn_rcpf(1.f + __expf(-uu[0][0])) * uu[1][0], a1 = uu[0][1] * __builtin_amdgcn_rcpf(1.f + __expf(-uu[0][1])) * uu[1][1];
;                       const float a2 = uu[0][2] * __builtin_amdgcn_rcpf(1.f + __expf(-uu[0][2])) * uu[1][2], a3 = uu[0][3] * __builtin_amdgcn_rcpf(1.f + __expf(-uu[0][3])) * uu[1][3];
;                       o.x = cvt_pk_bf16(a0, a1); o.y = cvt_pk_bf16(a2, a3); }
;                     *(u32x2v*)(ACT + (size_t)(row0 + ai * HALF + m * 16) * 5632 + u.pn * 128 + cidx + 4 * n) = o;
	v_fmac_f32_dpp v166, v8, v112 row_shr:1 row_mask:0xf bank_mask:0xf
	v_fmac_f32_dpp v167, v9, v113 row_shr:1 row_mask:0xf bank_mask:0xf
	v_fmac_f32_dpp v168, v10, v114 row_shr:1 row_mask:0xf bank_mask:0xf
	v_fmac_f32_dpp v169, v11, v115 row_shr:1 row_mask:0xf bank_mask:0xf
	v_fmac_f32_dpp v162, v12, v96 row_shr:2 row_mask:0xf bank_mask:0xf
	v_fmac_f32_dpp v163, v13, v97 row_shr:2 row_mask:0xf bank_mask:0xf
	v_fmac_f32_dpp v164, v14, v98 row_shr:2 row_mask:0xf bank_mask:0xf
	v_fmac_f32_dpp v165, v15, v99 row_shr:2 row_mask:0xf bank_mask:0xf
	v_fmac_f32_dpp v166, v8, v108 row_shr:2 row_mask:0xf bank_mask:0xf
	v_fmac_f32_dpp v167, v9, v109 row_shr:2 row_mask:0xf bank_mask:0xf
	v_fmac_f32_dpp v168, v10, v110 row_shr:2 row_mask:0xf bank_mask:0xf
	v_fmac_f32_dpp v169, v11, v111 row_shr:2 row_mask:0xf bank_mask:0xf
	v_fmac_f32_dpp v162, v20, v100 row_shl:15 row_mask:0xf bank_mask:0xf
	v_fmac_f32_dpp v163, v21, v101 row_shl:15 row_mask:0xf bank_mask:0xf
	v_fmac_f32_dpp v164, v22, v102 row_shl:15 row_mask:0xf bank_mask:0xf
	v_fmac_f32_dpp v165, v23, v103 row_shl:15 row_mask:0xf bank_mask:0xf
	v_fmac_f32_dpp v166, v16, v112 row_shl:15 row_mask:0xf bank_mask:0xf
	v_fmac_f32_dpp v167, v17, v113 row_shl:15 row_mask:0xf bank_mask:0xf
	v_fmac_f32_dpp v168, v18, v114 row_shl:15 row_mask:0xf bank_mask:0xf
	v_fmac_f32_dpp v169, v19, v115 row_shl:15 row_mask:0xf bank_mask:0xf
	v_fmac_f32_dpp v162, v20, v96 row_shl:14 row_mask:0xf bank_mask:0xf
	v_fmac_f32_dpp v163, v21, v97 row_shl:14 row_mask:0xf bank_mask:0xf
	v_fmac_f32_dpp v164, v22, v98 row_shl:14 row_mask:0xf bank_mask:0xf
	v_fmac_f32_dpp v165, v23, v99 row_shl:14 row_mask:0xf bank_mask:0xf
	v_fmac_f32_dpp v166, v16, v108 row_shl:14 row_mask:0xf bank_mask:0xf
	v_fmac_f32_dpp v167, v17, v109 row_shl:14 row_mask:0xf bank_mask:0xf
	v_fmac_f32_dpp v168, v18, v110 row_shl:14 row_mask:0xf bank_mask:0xf
	v_fmac_f32_dpp v169, v19, v111 row_shl:14 row_mask:0xf bank_mask:0xf
	v_mul_f32_e32 v230, 0xbfb8aa3b, v162
	v_mul_f32_e32 v231, 0xbfb8aa3b, v163
	v_mul_f32_e32 v232, 0xbfb8aa3b, v164
	v_mul_f32_e32 v233, 0xbfb8aa3b, v165
	v_exp_f32_e32 v230, v230
	v_exp_f32_e32 v231, v231
	v_exp_f32_e32 v232, v232
	v_exp_f32_e32 v233, v233
	v_add_f32_e32 v230, 1.0, v230
	v_add_f32_e32 v231, 1.0, v231
	v_add_f32_e32 v232, 1.0, v232
	v_add_f32_e32 v233, 1.0, v233
	v_rcp_f32_e32 v230, v230
	v_rcp_f32_e32 v231, v231
	v_rcp_f32_e32 v232, v232
	v_rcp_f32_e32 v233, v233
	v_mul_f32_e32 v230, v162, v230
	v_mul_f32_e32 v231, v163, v231
	v_mul_f32_e32 v232, v164, v232
	v_mul_f32_e32 v233, v165, v233
	v_mul_f32_e32 v230, v230, v166
	v_mul_f32_e32 v231, v231, v167
	v_mul_f32_e32 v232, v232, v168
	v_mul_f32_e32 v233, v233, v169
	v_mov_b32_e32 v88, v200
	v_mov_b32_e32 v89, v201
	v_cvt_pk_bf16_f32 v90, v230, v231
	v_cvt_pk_bf16_f32 v91, v232, v233
	s_mov_b32 s8, 0x1b8000
	v_lshl_add_u64 v[234:235], v[246:247], 0, s[8:9]
	global_store_dwordx4 v[234:235], v[88:91], off
	v_pk_mul_f32 v[4:5], v[4:5], v[196:197] op_sel_hi:[1,0]
	v_pk_mul_f32 v[6:7], v[6:7], v[196:197] op_sel_hi:[1,0]
	v_pk_mul_f32 v[0:1], v[0:1], v[196:197] op_sel_hi:[1,0]
	v_pk_mul_f32 v[2:3], v[2:3], v[196:197] op_sel_hi:[1,0]
	v_pk_mul_f32 v[162:163], v[4:5], v[104:105]
	v_pk_mul_f32 v[164:165], v[6:7], v[106:107]
	v_pk_mul_f32 v[166:167], v[0:1], v[116:117]
	v_pk_mul_f32 v[168:169], v[2:3], v[118:119]
	v_fmac_f32_dpp v162, v4, v100 row_shr:1 row_mask:0xf bank_mask:0xf
	v_fmac_f32_dpp v163, v5, v101 row_shr:1 row_mask:0xf bank_mask:0xf
	v_fmac_f32_dpp v164, v6, v102 row_shr:1 row_mask:0xf bank_mask:0xf
	v_fmac_f32_dpp v165, v7, v103 row_shr:1 row_mask:0xf bank_mask:0xf
	v_fmac_f32_dpp v166, v0, v112 row_shr:1 row_mask:0xf bank_mask:0xf
	v_fmac_f32_dpp v167, v1, v113 row_shr:1 row_mask:0xf bank_mask:0xf
	v_fmac_f32_dpp v168, v2, v114 row_shr:1 row_mask:0xf bank_mask:0xf
	v_fmac_f32_dpp v169, v3, v115 row_shr:1 row_mask:0xf bank_mask:0xf
	v_fmac_f32_dpp v162, v4, v96 row_shr:2 row_mask:0xf bank_mask:0xf
	v_fmac_f32_dpp v163, v5, v97 row_shr:2 row_mask:0xf bank_mask:0xf
	v_fmac_f32_dpp v164, v6, v98 row_shr:2 row_mask:0xf bank_mask:0xf
	v_fmac_f32_dpp v165, v7, v99 row_shr:2 row_mask:0xf bank_mask:0xf
	v_fmac_f32_dpp v166, v0, v108 row_shr:2 row_mask:0xf bank_mask:0xf
	v_fmac_f32_dpp v167, v1, v109 row_shr:2 row_mask:0xf bank_mask:0xf
	v_fmac_f32_dpp v168, v2, v110 row_shr:2 row_mask:0xf bank_mask:0xf
	v_fmac_f32_dpp v169, v3, v111 row_shr:2 row_mask:0xf bank_mask:0xf
	v_fmac_f32_dpp v162, v12, v100 row_shl:15 row_mask:0xf bank_mask:0xf
	v_fmac_f32_dpp v163, v13, v101 row_shl:15 row_mask:0xf bank_mask:0xf
	v_fmac_f32_dpp v164, v14, v102 row_shl:15 row_mask:0xf bank_mask:0xf
	v_fmac_f32_dpp v165, v15, v103 row_shl:15 row_mask:0xf bank_mask:0xf
	v_fmac_f32_dpp v166, v8, v112 row_shl:15 row_mask:0xf bank_mask:0xf
	v_fmac_f32_dpp v167, v9, v113 row_shl:15 row_mask:0xf bank_mask:0xf
	v_fmac_f32_dpp v168, v10, v114 row_shl:15 row_mask:0xf bank_mask:0xf
	v_fmac_f32_dpp v169, v11, v115 row_shl:15 row_mask:0xf bank_mask:0xf
	v_fmac_f32_dpp v162, v12, v96 row_shl:14 row_mask:0xf bank_mask:0xf
	v_fmac_f32_dpp v163, v13, v97 row_shl:14 row_mask:0xf bank_mask:0xf
	v_fmac_f32_dpp v164, v14, v98 row_shl:14 row_mask:0xf bank_mask:0xf
	v_fmac_f32_dpp v165, v15, v99 row_shl:14 row_mask:0xf bank_mask:0xf
	v_fmac_f32_dpp v166, v8, v108 row_shl:14 row_mask:0xf bank_mask:0xf
	v_fmac_f32_dpp v167, v9, v109 row_shl:14 row_mask:0xf bank_mask:0xf
	v_fmac_f32_dpp v168, v10, v110 row_shl:14 row_mask:0xf bank_mask:0xf
	v_fmac_f32_dpp v169, v11, v111 row_shl:14 row_mask:0xf bank_mask:0xf
	v_mul_f32_e32 v230, 0xbfb8aa3b, v162
	v_mul_f32_e32 v231, 0xbfb8aa3b, v163
	v_mul_f32_e32 v232, 0xbfb8aa3b, v164
	v_mul_f32_e32 v233, 0xbfb8aa3b, v165
	v_exp_f32_e32 v230, v230
	v_exp_f32_e32 v231, v231
	v_exp_f32_e32 v232, v232
	v_exp_f32_e32 v233, v233
	v_add_f32_e32 v230, 1.0, v230
	v_add_f32_e32 v231, 1.0, v231
	v_add_f32_e32 v232, 1.0, v232
	v_add_f32_e32 v233, 1.0, v233
	v_rcp_f32_e32 v230, v230
	v_rcp_f32_e32 v231, v231
	v_rcp_f32_e32 v232, v232
	v_rcp_f32_e32 v233, v233
	v_mul_f32_e32 v230, v162, v230
	v_mul_f32_e32 v231, v163, v231
	v_mul_f32_e32 v232, v164, v232
	v_mul_f32_e32 v233, v165, v233
	v_mul_f32_e32 v230, v230, v166
	v_mul_f32_e32 v231, v231, v167
	v_mul_f32_e32 v232, v232, v168
	v_mul_f32_e32 v233, v233, v169
	v_mov_b32_e32 v92, v248
	v_mov_b32_e32 v93, v249
	v_cvt_pk_bf16_f32 v94, v230, v231
	v_cvt_pk_bf16_f32 v95, v232, v233
	s_mov_b32 s8, 0x1e4000
	v_lshl_add_u64 v[234:235], v[246:247], 0, s[8:9]
	global_store_dwordx4 v[234:235], v[92:95], off
	v_readlane_b32 s8, v255, 44
	s_and_b32 s8, s8, 1
	s_xor_b32 s8, s8, 1
	s_and_b32 s9, s6, 2
	s_or_b32 s8, s8, s9
	v_writelane_b32 v255, s8, 44
	s_andn2_b64 vcc, exec, s[6:7]
	s_mov_b64 s[6:7], -1
	s_cbranch_vccnz .LBB0_1881
	v_readlane_b32 s6, v255, 11
	v_readlane_b32 s7, v255, 12
	s_andn2_b64 vcc, exec, s[6:7]
	s_cbranch_vccnz .LBB0_1880
	s_barrier
	s_branch .LBB0_1880
